# gemm96 (G2a/G2b/G3) mainloops: register staging replaced by whole-line LDS-DMA into two 28 KB stages
# speedup vs baseline: 1.0475x; 1.0037x over previous
.LBB1_80:
	v_readlane_b32 s4, v242, 0
	s_lshl_b32 s5, s2, 3
	s_and_b32 s6, s4, 7
	s_or_b32 s5, s6, s5
	s_mul_i32 s5, s5, s55
	s_ashr_i32 s4, s4, 3
	s_add_i32 s4, s5, s4
	s_cmpk_gt_i32 s4, 0x57f
	s_mov_b64 s[30:31], -1
	s_cbranch_scc1 .LBB1_79
	s_ashr_i32 s5, s4, 31
	s_lshr_b32 s5, s5, 26
	s_add_i32 s5, s4, s5
	s_lshr_b32 s6, s5, 3
	s_andn2_b32 s5, s5, 63
	s_sub_i32 s4, s4, s5
	s_ashr_i32 s5, s4, 31
	s_lshr_b32 s5, s5, 29
	s_add_i32 s7, s4, s5
	s_and_b32 s5, s7, 0x7fffff8
	s_and_b32 s6, s6, 0x1ffffff8
	s_sub_i32 s4, s4, s5
	v_mov_b32_e32 v90, v162
	s_add_i32 s5, s4, s6
	s_load_dwordx16 s[40:55], s[0:1], 0x140
	s_mulk_i32 s5, 0x60
	v_ashrrev_i32_e32 v44, 3, v90
	v_add_u32_e32 v0, s5, v44
	v_ashrrev_i32_e32 v1, 31, v0
	v_lshlrev_b64 v[0:1], 11, v[0:1]
	s_lshl_b32 s4, s7, 4
	s_waitcnt lgkmcnt(0)
	v_lshl_add_u64 v[0:1], s[50:51], 0, v[0:1]
	v_lshlrev_b32_e32 v2, 4, v90
	s_load_dwordx16 s[40:55], s[0:1], 0xc0
	s_and_b32 s4, s4, 0xffffff80
	v_and_b32_e32 v128, 0x70, v2
	v_lshl_add_u64 v[76:77], v[0:1], 0, v[128:129]
	v_add_u32_e32 v0, s4, v44
	v_ashrrev_i32_e32 v1, 31, v0
	v_lshlrev_b64 v[0:1], 11, v[0:1]
	s_waitcnt lgkmcnt(0)
	v_lshl_add_u64 v[0:1], s[50:51], 0, v[0:1]
	s_mov_b32 s6, 0x10000
	v_lshl_add_u64 v[78:79], v[0:1], 0, v[128:129]
	v_add_co_u32_e32 v0, vcc, s6, v76
	s_mov_b32 s7, 0x30000
	s_nop 0
	v_addc_co_u32_e32 v1, vcc, 0, v77, vcc
	v_add_co_u32_e32 v30, vcc, s6, v78
	s_mov_b32 s6, 0x20000
	s_nop 0
	v_addc_co_u32_e32 v31, vcc, 0, v79, vcc
	v_add_co_u32_e32 v32, vcc, s6, v78
	s_nop 0
	v_addc_co_u32_e32 v33, vcc, 0, v79, vcc
	v_add_co_u32_e32 v34, vcc, s7, v78
	s_nop 0
	v_addc_co_u32_e32 v35, vcc, 0, v79, vcc
	v_add_co_u32_e32 v36, vcc, s6, v76
	v_addc_co_u32_e32 v37, vcc, 0, v77, vcc
	s_barrier
	s_nop 0
	v_ashrrev_i32_e32 v1, 7, v90
	s_movk_i32 s8, 0x90
	v_and_b32_e32 v92, 15, v90
	v_mul_lo_u32 v31, v44, s8
	v_mul_lo_u32 v93, v1, 48
	v_bfe_u32 v91, v90, 4, 2
	v_and_b32_e32 v30, 0x4f, v90
	v_add3_u32 v94, v128, v31, 16
	v_or_b32_e32 v31, v93, v92
	v_mov_b32_e32 v0, 0
	v_lshl_add_u32 v1, v91, 4, 16
	v_mul_u32_u24_e32 v30, 0x90, v30
	v_mul_lo_u32 v31, v31, s8
	s_mov_b64 s[8:9], 0x10000
	s_mov_b64 s[10:11], 0x20000
	s_mov_b64 s[12:13], 0x30000
	s_mov_b32 s7, 0
	s_movk_i32 s6, 0x80
	v_add_u32_e32 v95, 0xd800, v94
	v_add_u32_e32 v96, v1, v31
	v_lshl_add_u64 v[80:81], v[78:79], 0, s[8:9]
	v_lshl_add_u64 v[82:83], v[78:79], 0, s[10:11]
	v_lshl_add_u64 v[84:85], v[78:79], 0, s[12:13]
	v_lshl_add_u64 v[86:87], v[76:77], 0, s[8:9]
	v_lshl_add_u64 v[88:89], v[76:77], 0, s[10:11]
	v_add_u32_e32 v97, v1, v30
	v_mov_b32_e32 v1, v0
	v_mov_b32_e32 v30, v0
	v_mov_b32_e32 v31, v0
	v_mov_b32_e32 v32, v0
	v_mov_b32_e32 v33, v0
	v_mov_b32_e32 v34, v0
	v_mov_b32_e32 v35, v0
	v_mov_b32_e32 v44, v0
	v_mov_b32_e32 v45, v0
	v_mov_b32_e32 v46, v0
	v_mov_b32_e32 v47, v0
	v_mov_b32_e32 v68, v0
	v_mov_b32_e32 v69, v0
	v_mov_b32_e32 v70, v0
	v_mov_b32_e32 v71, v0
	v_mov_b32_e32 v72, v0
	v_mov_b32_e32 v73, v0
	v_mov_b32_e32 v74, v0
	v_mov_b32_e32 v75, v0
	s_waitcnt vmcnt(12)
	s_waitcnt vmcnt(11)
	s_waitcnt vmcnt(10)
	s_waitcnt vmcnt(9)
	s_waitcnt vmcnt(8)
	s_waitcnt vmcnt(7)
	v_mov_b32_e32 v2, v0
	v_mov_b32_e32 v3, v0
	v_mov_b32_e32 v4, v0
	v_mov_b32_e32 v5, v0
	v_mov_b32_e32 v6, v0
	v_mov_b32_e32 v7, v0
	v_mov_b32_e32 v8, v0
	v_mov_b32_e32 v9, v0
	v_mov_b32_e32 v10, v0
	v_mov_b32_e32 v11, v0
	v_mov_b32_e32 v12, v0
	v_mov_b32_e32 v13, v0
	v_mov_b32_e32 v14, v0
	v_mov_b32_e32 v15, v0
	v_mov_b32_e32 v16, v0
	v_mov_b32_e32 v17, v0
	v_mov_b32_e32 v18, v0
	v_mov_b32_e32 v19, v0
	v_mov_b32_e32 v20, v0
	v_mov_b32_e32 v21, v0
	v_mov_b32_e32 v22, v0
	v_mov_b32_e32 v23, v0
	v_mov_b32_e32 v24, v0
	v_mov_b32_e32 v25, v0
	v_mov_b32_e32 v26, v0
	v_mov_b32_e32 v27, v0
	v_mov_b32_e32 v28, v0
	v_mov_b32_e32 v29, v0
	s_waitcnt lgkmcnt(0)
	s_barrier
	v_and_b32_e32 v204, 15, v168
	v_lshrrev_b32_e32 v205, 4, v168
	v_bfe_u32 v206, v168, 1, 3
	v_xor_b32_e32 v205, v205, v206
	v_lshlrev_b32_e32 v205, 4, v205
	v_readfirstlane_b32 s19, v162
	v_readfirstlane_b32 s8, v76
	v_readfirstlane_b32 s9, v77
	v_readfirstlane_b32 s10, v78
	v_readfirstlane_b32 s11, v79
	s_lshr_b32 s19, s19, 6
	s_lshr_b32 s16, s19, 1
	s_and_b32 s17, s19, 1
	s_mul_i32 s16, s16, 48
	v_add_u32_e32 v206, s16, v204
	v_lshl_add_u32 v232, v206, 7, v205
	v_xor_b32_e32 v233, 64, v232
	v_add_u32_e32 v232, 16, v232
	v_add_u32_e32 v233, 16, v233
	v_lshl_add_u32 v206, s17, 6, v204
	v_lshl_add_u32 v234, v206, 7, v205
	v_xor_b32_e32 v235, 64, v234
	v_add_u32_e32 v234, 0x3010, v234
	v_add_u32_e32 v235, 0x3010, v235
	v_lshrrev_b32_e32 v206, 3, v168
	v_and_b32_e32 v207, 7, v168
	v_lshrrev_b32_e32 v204, 1, v206
	v_xor_b32_e32 v207, v207, v204
	v_lshlrev_b32_e32 v207, 4, v207
	v_lshl_add_u32 v236, v206, 11, v207
	v_xor_b32_e32 v237, 64, v236
	s_and_b32 s17, s19, 1
	s_cmp_eq_u32 s17, 0
	s_cselect_b64 vcc, -1, 0
	s_nop 3
	v_cndmask_b32_e32 v238, v237, v236, vcc
	v_cndmask_b32_e32 v239, v236, v237, vcc
	s_mul_i32 s16, s19, 0x8000
	s_add_u32 s8, s8, s16
	s_addc_u32 s9, s9, 0
	s_mul_i32 s16, s19, 0xc000
	s_add_u32 s10, s10, s16
	s_addc_u32 s11, s11, 0
	s_mul_i32 s16, s19, 0xc00
	s_lshl_b32 s17, s19, 12
	s_add_i32 m0, s16, 0x10
	s_nop 0
	global_load_lds_dwordx4 v238, s[8:9]
	s_add_i32 m0, s16, 0x410
	s_add_u32 s12, s8, 0x4000
	s_addc_u32 s13, s9, 0
	global_load_lds_dwordx4 v239, s[12:13]
	s_add_i32 m0, s16, 0x810
	s_add_u32 s12, s8, 0x8000
	s_addc_u32 s13, s9, 0
	global_load_lds_dwordx4 v238, s[12:13]
	s_add_i32 m0, s17, 0x3010
	s_nop 0
	global_load_lds_dwordx4 v236, s[10:11]
	s_add_i32 m0, s17, 0x3410
	s_add_u32 s12, s10, 0x4000
	s_addc_u32 s13, s11, 0
	global_load_lds_dwordx4 v237, s[12:13]
	s_add_i32 m0, s17, 0x3810
	s_add_u32 s12, s10, 0x8000
	s_addc_u32 s13, s11, 0
	global_load_lds_dwordx4 v236, s[12:13]
	s_add_i32 m0, s17, 0x3c10
	s_add_u32 s12, s10, 0xc000
	s_addc_u32 s13, s11, 0
	global_load_lds_dwordx4 v237, s[12:13]
	s_mov_b32 s18, 0
	s_waitcnt vmcnt(0)
	s_barrier
	s_setprio 1
.LBB1_82:
	s_lshl_b32 s19, s18, 8
	s_add_i32 s19, s19, 0x80
	s_min_u32 s19, s19, 0x780
	s_add_u32 s40, s8, s19
	s_addc_u32 s41, s9, 0
	s_add_u32 s42, s10, s19
	s_addc_u32 s43, s11, 0
	ds_read_b128 v[142:145], v234 offset:0
	ds_read_b128 v[146:149], v234 offset:2048
	ds_read_b128 v[150:153], v234 offset:4096
	ds_read_b128 v[154:157], v234 offset:6144
	ds_read_b128 v[130:133], v232 offset:0
	ds_read_b128 v[134:137], v232 offset:2048
	ds_read_b128 v[138:141], v232 offset:4096
	ds_read_b128 v[216:219], v235 offset:0
	ds_read_b128 v[220:223], v235 offset:2048
	ds_read_b128 v[224:227], v235 offset:4096
	ds_read_b128 v[228:231], v235 offset:6144
	ds_read_b128 v[188:191], v233 offset:0
	ds_read_b128 v[192:195], v233 offset:2048
	ds_read_b128 v[196:199], v233 offset:4096
	s_waitcnt lgkmcnt(9)
	s_add_i32 m0, s16, 0x7010
	s_nop 0
	v_mfma_f32_16x16x32_bf16 v[72:75], v[142:145], v[130:133], v[72:75]
	global_load_lds_dwordx4 v238, s[40:41]
	s_add_i32 m0, s16, 0x7410
	s_add_u32 s12, s40, 0x4000
	s_addc_u32 s13, s41, 0
	v_mfma_f32_16x16x32_bf16 v[68:71], v[146:149], v[130:133], v[68:71]
	global_load_lds_dwordx4 v239, s[12:13]
	v_mfma_f32_16x16x32_bf16 v[44:47], v[150:153], v[130:133], v[44:47]
	v_mfma_f32_16x16x32_bf16 v[32:35], v[154:157], v[130:133], v[32:35]
	s_waitcnt lgkmcnt(8)
	s_add_i32 m0, s16, 0x7810
	s_add_u32 s12, s40, 0x8000
	s_addc_u32 s13, s41, 0
	v_mfma_f32_16x16x32_bf16 v[28:31], v[142:145], v[134:137], v[28:31]
	v_mfma_f32_16x16x32_bf16 v[24:27], v[146:149], v[134:137], v[24:27]
	global_load_lds_dwordx4 v238, s[12:13]
	v_mfma_f32_16x16x32_bf16 v[20:23], v[150:153], v[134:137], v[20:23]
	v_mfma_f32_16x16x32_bf16 v[16:19], v[154:157], v[134:137], v[16:19]
	s_waitcnt lgkmcnt(7)
	s_add_i32 m0, s17, 0xa010
	s_nop 0
	v_mfma_f32_16x16x32_bf16 v[12:15], v[142:145], v[138:141], v[12:15]
	v_mfma_f32_16x16x32_bf16 v[8:11], v[146:149], v[138:141], v[8:11]
	global_load_lds_dwordx4 v236, s[42:43]
	v_mfma_f32_16x16x32_bf16 v[4:7], v[150:153], v[138:141], v[4:7]
	v_mfma_f32_16x16x32_bf16 v[0:3], v[154:157], v[138:141], v[0:3]
	s_waitcnt lgkmcnt(2)
	s_add_i32 m0, s17, 0xa410
	s_add_u32 s12, s42, 0x4000
	s_addc_u32 s13, s43, 0
	v_mfma_f32_16x16x32_bf16 v[72:75], v[216:219], v[188:191], v[72:75]
	v_mfma_f32_16x16x32_bf16 v[68:71], v[220:223], v[188:191], v[68:71]
	global_load_lds_dwordx4 v237, s[12:13]
	v_mfma_f32_16x16x32_bf16 v[44:47], v[224:227], v[188:191], v[44:47]
	v_mfma_f32_16x16x32_bf16 v[32:35], v[228:231], v[188:191], v[32:35]
	s_waitcnt lgkmcnt(1)
	s_add_i32 m0, s17, 0xa810
	s_add_u32 s12, s42, 0x8000
	s_addc_u32 s13, s43, 0
	v_mfma_f32_16x16x32_bf16 v[28:31], v[216:219], v[192:195], v[28:31]
	v_mfma_f32_16x16x32_bf16 v[24:27], v[220:223], v[192:195], v[24:27]
	global_load_lds_dwordx4 v236, s[12:13]
	v_mfma_f32_16x16x32_bf16 v[20:23], v[224:227], v[192:195], v[20:23]
	v_mfma_f32_16x16x32_bf16 v[16:19], v[228:231], v[192:195], v[16:19]
	s_waitcnt lgkmcnt(0)
	s_add_i32 m0, s17, 0xac10
	s_add_u32 s12, s42, 0xc000
	s_addc_u32 s13, s43, 0
	v_mfma_f32_16x16x32_bf16 v[12:15], v[216:219], v[196:199], v[12:15]
	v_mfma_f32_16x16x32_bf16 v[8:11], v[220:223], v[196:199], v[8:11]
	global_load_lds_dwordx4 v237, s[12:13]
	v_mfma_f32_16x16x32_bf16 v[4:7], v[224:227], v[196:199], v[4:7]
	v_mfma_f32_16x16x32_bf16 v[0:3], v[228:231], v[196:199], v[0:3]
	s_waitcnt vmcnt(0)
	s_barrier
	s_lshl_b32 s19, s18, 8
	s_add_i32 s19, s19, 0x100
	s_min_u32 s19, s19, 0x780
	s_add_u32 s40, s8, s19
	s_addc_u32 s41, s9, 0
	s_add_u32 s42, s10, s19
	s_addc_u32 s43, s11, 0
	ds_read_b128 v[142:145], v234 offset:28672
	ds_read_b128 v[146:149], v234 offset:30720
	ds_read_b128 v[150:153], v234 offset:32768
	ds_read_b128 v[154:157], v234 offset:34816
	ds_read_b128 v[130:133], v232 offset:28672
	ds_read_b128 v[134:137], v232 offset:30720
	ds_read_b128 v[138:141], v232 offset:32768
	ds_read_b128 v[216:219], v235 offset:28672
	ds_read_b128 v[220:223], v235 offset:30720
	ds_read_b128 v[224:227], v235 offset:32768
	ds_read_b128 v[228:231], v235 offset:34816
	ds_read_b128 v[188:191], v233 offset:28672
	ds_read_b128 v[192:195], v233 offset:30720
	ds_read_b128 v[196:199], v233 offset:32768
	s_waitcnt lgkmcnt(9)
	s_add_i32 m0, s16, 0x10
	s_nop 0
	v_mfma_f32_16x16x32_bf16 v[72:75], v[142:145], v[130:133], v[72:75]
	global_load_lds_dwordx4 v238, s[40:41]
	s_add_i32 m0, s16, 0x410
	s_add_u32 s12, s40, 0x4000
	s_addc_u32 s13, s41, 0
	v_mfma_f32_16x16x32_bf16 v[68:71], v[146:149], v[130:133], v[68:71]
	global_load_lds_dwordx4 v239, s[12:13]
	v_mfma_f32_16x16x32_bf16 v[44:47], v[150:153], v[130:133], v[44:47]
	v_mfma_f32_16x16x32_bf16 v[32:35], v[154:157], v[130:133], v[32:35]
	s_waitcnt lgkmcnt(8)
	s_add_i32 m0, s16, 0x810
	s_add_u32 s12, s40, 0x8000
	s_addc_u32 s13, s41, 0
	v_mfma_f32_16x16x32_bf16 v[28:31], v[142:145], v[134:137], v[28:31]
	v_mfma_f32_16x16x32_bf16 v[24:27], v[146:149], v[134:137], v[24:27]
	global_load_lds_dwordx4 v238, s[12:13]
	v_mfma_f32_16x16x32_bf16 v[20:23], v[150:153], v[134:137], v[20:23]
	v_mfma_f32_16x16x32_bf16 v[16:19], v[154:157], v[134:137], v[16:19]
	s_waitcnt lgkmcnt(7)
	s_add_i32 m0, s17, 0x3010
	s_nop 0
	v_mfma_f32_16x16x32_bf16 v[12:15], v[142:145], v[138:141], v[12:15]
	v_mfma_f32_16x16x32_bf16 v[8:11], v[146:149], v[138:141], v[8:11]
	global_load_lds_dwordx4 v236, s[42:43]
	v_mfma_f32_16x16x32_bf16 v[4:7], v[150:153], v[138:141], v[4:7]
	v_mfma_f32_16x16x32_bf16 v[0:3], v[154:157], v[138:141], v[0:3]
	s_waitcnt lgkmcnt(2)
	s_add_i32 m0, s17, 0x3410
	s_add_u32 s12, s42, 0x4000
	s_addc_u32 s13, s43, 0
	v_mfma_f32_16x16x32_bf16 v[72:75], v[216:219], v[188:191], v[72:75]
	v_mfma_f32_16x16x32_bf16 v[68:71], v[220:223], v[188:191], v[68:71]
	global_load_lds_dwordx4 v237, s[12:13]
	v_mfma_f32_16x16x32_bf16 v[44:47], v[224:227], v[188:191], v[44:47]
	v_mfma_f32_16x16x32_bf16 v[32:35], v[228:231], v[188:191], v[32:35]
	s_waitcnt lgkmcnt(1)
	s_add_i32 m0, s17, 0x3810
	s_add_u32 s12, s42, 0x8000
	s_addc_u32 s13, s43, 0
	v_mfma_f32_16x16x32_bf16 v[28:31], v[216:219], v[192:195], v[28:31]
	v_mfma_f32_16x16x32_bf16 v[24:27], v[220:223], v[192:195], v[24:27]
	global_load_lds_dwordx4 v236, s[12:13]
	v_mfma_f32_16x16x32_bf16 v[20:23], v[224:227], v[192:195], v[20:23]
	v_mfma_f32_16x16x32_bf16 v[16:19], v[228:231], v[192:195], v[16:19]
	s_waitcnt lgkmcnt(0)
	s_add_i32 m0, s17, 0x3c10
	s_add_u32 s12, s42, 0xc000
	s_addc_u32 s13, s43, 0
	v_mfma_f32_16x16x32_bf16 v[12:15], v[216:219], v[196:199], v[12:15]
	v_mfma_f32_16x16x32_bf16 v[8:11], v[220:223], v[196:199], v[8:11]
	global_load_lds_dwordx4 v237, s[12:13]
	v_mfma_f32_16x16x32_bf16 v[4:7], v[224:227], v[196:199], v[4:7]
	v_mfma_f32_16x16x32_bf16 v[0:3], v[228:231], v[196:199], v[0:3]
	s_waitcnt vmcnt(0)
	s_barrier
	s_add_i32 s18, s18, 1
	s_cmp_eq_u32 s18, 8
	s_cbranch_scc0 .LBB1_82
	s_setprio 0
	s_waitcnt vmcnt(6)
	v_or_b32_e32 v37, s5, v92
	v_and_b32_e32 v36, 64, v90
	s_waitcnt vmcnt(5)
	v_add_u32_e32 v40, v37, v93
	v_lshlrev_b32_e32 v37, 2, v91
	s_waitcnt vmcnt(2)
	v_or3_b32 v56, v37, v36, s4
	s_movk_i32 s4, 0x4000
	v_cmp_gt_u32_e32 vcc, s4, v40
	s_movk_i32 s5, 0x1fff
	v_ashrrev_i32_e32 v41, 31, v40
	v_cndmask_b32_e32 v52, v176, v177, vcc
	v_cmp_lt_i32_e32 vcc, s5, v40
	v_lshlrev_b64 v[38:39], 12, v[40:41]
	v_ashrrev_i32_e32 v57, 31, v56
	v_cndmask_b32_e32 v41, 0, v52, vcc
	v_readlane_b32 s10, v241, 32
	v_lshl_add_u64 v[42:43], s[70:71], 0, v[38:39]
	v_lshlrev_b64 v[36:37], 2, v[56:57]
	v_lshlrev_b32_e32 v128, 2, v41
	v_readlane_b32 s11, v241, 33
	v_lshl_add_u64 v[58:59], v[42:43], 0, v[36:37]
	s_mov_b64 s[8:9], 0x2000
	v_lshl_add_u64 v[42:43], s[10:11], 0, v[128:129]
	s_waitcnt vmcnt(1)
	v_lshl_add_u64 v[60:61], v[42:43], 0, s[8:9]
	v_lshl_add_u64 v[42:43], v[60:61], 0, v[36:37]
	global_load_dwordx4 v[52:55], v[42:43], off
	global_load_dwordx4 v[48:51], v[58:59], off
	v_lshl_add_u64 v[38:39], s[72:73], 0, v[38:39]
	v_lshl_add_u64 v[62:63], v[38:39], 0, v[36:37]
	v_or_b32_e32 v38, 16, v56
	s_mov_b32 s6, 0x3fd744fd
	v_ashrrev_i32_e32 v39, 31, v38
	v_lshlrev_b64 v[38:39], 2, v[38:39]
	s_add_i32 s2, s2, 1
	s_mov_b64 s[30:31], 0
	v_readlane_b32 s55, v241, 23
	s_waitcnt vmcnt(1)
	v_pk_mul_f32 v[42:43], v[74:75], v[54:55]
	v_pk_mul_f32 v[52:53], v[72:73], v[52:53]
	s_waitcnt vmcnt(0)
	v_pk_fma_f32 v[50:51], v[50:51], s[6:7], v[42:43] op_sel_hi:[1,0,1]
	v_pk_fma_f32 v[48:49], v[48:49], s[6:7], v[52:53] op_sel_hi:[1,0,1]
	global_store_dwordx4 v[62:63], v[48:51], off
	v_lshl_add_u64 v[42:43], v[60:61], 0, v[38:39]
	global_load_dwordx4 v[52:55], v[42:43], off
	global_load_dwordx4 v[48:51], v[58:59], off offset:64
	s_waitcnt vmcnt(1)
	v_pk_mul_f32 v[42:43], v[70:71], v[54:55]
	s_waitcnt vmcnt(0)
	v_pk_fma_f32 v[50:51], v[50:51], s[6:7], v[42:43] op_sel_hi:[1,0,1]
	v_or_b32_e32 v42, 32, v56
	v_pk_mul_f32 v[52:53], v[68:69], v[52:53]
	v_ashrrev_i32_e32 v43, 31, v42
	v_pk_fma_f32 v[48:49], v[48:49], s[6:7], v[52:53] op_sel_hi:[1,0,1]
	v_lshlrev_b64 v[42:43], 2, v[42:43]
	global_store_dwordx4 v[62:63], v[48:51], off offset:64
	v_lshl_add_u64 v[52:53], v[60:61], 0, v[42:43]
	global_load_dwordx4 v[52:55], v[52:53], off
	s_waitcnt vmcnt(0)
	v_pk_mul_f32 v[46:47], v[46:47], v[54:55]
	global_load_dwordx4 v[48:51], v[58:59], off offset:128
	v_pk_mul_f32 v[44:45], v[44:45], v[52:53]
	s_waitcnt vmcnt(0)
	v_pk_fma_f32 v[46:47], v[50:51], s[6:7], v[46:47] op_sel_hi:[1,0,1]
	v_pk_fma_f32 v[44:45], v[48:49], s[6:7], v[44:45] op_sel_hi:[1,0,1]
	global_store_dwordx4 v[62:63], v[44:47], off offset:128
	global_load_dwordx4 v[46:49], v[58:59], off offset:192
	s_nop 0
	v_or_b32_e32 v44, 48, v56
	v_ashrrev_i32_e32 v45, 31, v44
	v_lshlrev_b64 v[44:45], 2, v[44:45]
	v_lshl_add_u64 v[50:51], v[60:61], 0, v[44:45]
	global_load_dwordx4 v[50:53], v[50:51], off
	s_waitcnt vmcnt(0)
	v_pk_mul_f32 v[32:33], v[32:33], v[50:51]
	s_nop 0
	v_pk_fma_f32 v[32:33], v[46:47], s[6:7], v[32:33] op_sel_hi:[1,0,1]
	v_add_u32_e32 v46, 16, v40
	v_cmp_gt_u32_e32 vcc, s4, v46
	v_ashrrev_i32_e32 v47, 31, v46
	v_pk_mul_f32 v[34:35], v[34:35], v[52:53]
	v_cndmask_b32_e32 v41, v176, v177, vcc
	v_cmp_lt_i32_e32 vcc, s5, v46
	v_lshlrev_b64 v[50:51], 12, v[46:47]
	v_pk_fma_f32 v[34:35], v[48:49], s[6:7], v[34:35] op_sel_hi:[1,0,1]
	v_cndmask_b32_e32 v41, 0, v41, vcc
	v_lshlrev_b32_e32 v128, 2, v41
	v_lshl_add_u64 v[46:47], s[10:11], 0, v[128:129]
	v_lshl_add_u64 v[54:55], v[46:47], 0, s[8:9]
	global_store_dwordx4 v[62:63], v[32:35], off offset:192
	v_lshl_add_u64 v[46:47], v[54:55], 0, v[36:37]
	global_load_dwordx4 v[46:49], v[46:47], off
	v_lshl_add_u64 v[32:33], s[70:71], 0, v[50:51]
	v_lshl_add_u64 v[52:53], v[32:33], 0, v[36:37]
	global_load_dwordx4 v[32:35], v[52:53], off
	s_waitcnt vmcnt(1)
	v_pk_mul_f32 v[28:29], v[28:29], v[46:47]
	v_pk_mul_f32 v[30:31], v[30:31], v[48:49]
	s_waitcnt vmcnt(0)
	v_pk_fma_f32 v[28:29], v[32:33], s[6:7], v[28:29] op_sel_hi:[1,0,1]
	v_lshl_add_u64 v[32:33], s[72:73], 0, v[50:51]
	v_pk_fma_f32 v[30:31], v[34:35], s[6:7], v[30:31] op_sel_hi:[1,0,1]
	v_lshl_add_u64 v[46:47], v[32:33], 0, v[36:37]
	global_store_dwordx4 v[46:47], v[28:31], off
	v_lshl_add_u64 v[32:33], v[54:55], 0, v[38:39]
	global_load_dwordx4 v[32:35], v[32:33], off
	s_waitcnt vmcnt(0)
	v_pk_mul_f32 v[26:27], v[26:27], v[34:35]
	global_load_dwordx4 v[28:31], v[52:53], off offset:64
	v_pk_mul_f32 v[24:25], v[24:25], v[32:33]
	s_waitcnt vmcnt(0)
	v_pk_fma_f32 v[26:27], v[30:31], s[6:7], v[26:27] op_sel_hi:[1,0,1]
	v_pk_fma_f32 v[24:25], v[28:29], s[6:7], v[24:25] op_sel_hi:[1,0,1]
	global_store_dwordx4 v[46:47], v[24:27], off offset:64
	v_lshl_add_u64 v[28:29], v[54:55], 0, v[42:43]
	global_load_dwordx4 v[28:31], v[28:29], off
	s_waitcnt vmcnt(0)
	v_pk_mul_f32 v[22:23], v[22:23], v[30:31]
	global_load_dwordx4 v[24:27], v[52:53], off offset:128
	v_pk_mul_f32 v[20:21], v[20:21], v[28:29]
	s_waitcnt vmcnt(0)
	v_pk_fma_f32 v[22:23], v[26:27], s[6:7], v[22:23] op_sel_hi:[1,0,1]
	v_pk_fma_f32 v[20:21], v[24:25], s[6:7], v[20:21] op_sel_hi:[1,0,1]
	global_store_dwordx4 v[46:47], v[20:23], off offset:128
	v_lshl_add_u64 v[24:25], v[54:55], 0, v[44:45]
	global_load_dwordx4 v[24:27], v[24:25], off
	s_waitcnt vmcnt(0)
	v_pk_mul_f32 v[16:17], v[16:17], v[24:25]
	global_load_dwordx4 v[20:23], v[52:53], off offset:192
	v_pk_mul_f32 v[18:19], v[18:19], v[26:27]
	s_waitcnt vmcnt(0)
	v_pk_fma_f32 v[16:17], v[20:21], s[6:7], v[16:17] op_sel_hi:[1,0,1]
	v_add_u32_e32 v20, 32, v40
	v_cmp_gt_u32_e32 vcc, s4, v20
	v_pk_fma_f32 v[18:19], v[22:23], s[6:7], v[18:19] op_sel_hi:[1,0,1]
	v_ashrrev_i32_e32 v21, 31, v20
	v_cndmask_b32_e32 v22, v176, v177, vcc
	v_cmp_lt_i32_e32 vcc, s5, v20
	v_lshlrev_b64 v[24:25], 12, v[20:21]
	global_store_dwordx4 v[46:47], v[16:19], off offset:192
	v_cndmask_b32_e32 v20, 0, v22, vcc
	v_lshlrev_b32_e32 v128, 2, v20
	v_lshl_add_u64 v[20:21], s[10:11], 0, v[128:129]
	v_lshl_add_u64 v[28:29], v[20:21], 0, s[8:9]
	v_lshl_add_u64 v[16:17], s[70:71], 0, v[24:25]
	v_lshl_add_u64 v[20:21], v[28:29], 0, v[36:37]
	v_lshl_add_u64 v[26:27], v[16:17], 0, v[36:37]
	global_load_dwordx4 v[20:23], v[20:21], off
	s_waitcnt vmcnt(0)
	v_pk_mul_f32 v[12:13], v[12:13], v[20:21]
	global_load_dwordx4 v[16:19], v[26:27], off
	v_pk_mul_f32 v[14:15], v[14:15], v[22:23]
	s_waitcnt vmcnt(0)
	v_pk_fma_f32 v[12:13], v[16:17], s[6:7], v[12:13] op_sel_hi:[1,0,1]
	v_lshl_add_u64 v[16:17], s[72:73], 0, v[24:25]
	v_pk_fma_f32 v[14:15], v[18:19], s[6:7], v[14:15] op_sel_hi:[1,0,1]
	v_lshl_add_u64 v[20:21], v[16:17], 0, v[36:37]
	global_store_dwordx4 v[20:21], v[12:15], off
	v_lshl_add_u64 v[16:17], v[28:29], 0, v[38:39]
	global_load_dwordx4 v[16:19], v[16:17], off
	s_waitcnt vmcnt(0)
	v_pk_mul_f32 v[10:11], v[10:11], v[18:19]
	global_load_dwordx4 v[12:15], v[26:27], off offset:64
	v_pk_mul_f32 v[8:9], v[8:9], v[16:17]
	s_waitcnt vmcnt(0)
	v_pk_fma_f32 v[10:11], v[14:15], s[6:7], v[10:11] op_sel_hi:[1,0,1]
	v_pk_fma_f32 v[8:9], v[12:13], s[6:7], v[8:9] op_sel_hi:[1,0,1]
	global_store_dwordx4 v[20:21], v[8:11], off offset:64
	v_lshl_add_u64 v[12:13], v[28:29], 0, v[42:43]
	global_load_dwordx4 v[12:15], v[12:13], off
	s_waitcnt vmcnt(0)
	v_pk_mul_f32 v[6:7], v[6:7], v[14:15]
	global_load_dwordx4 v[8:11], v[26:27], off offset:128
	v_pk_mul_f32 v[4:5], v[4:5], v[12:13]
	s_waitcnt vmcnt(0)
	v_pk_fma_f32 v[6:7], v[10:11], s[6:7], v[6:7] op_sel_hi:[1,0,1]
	v_pk_fma_f32 v[4:5], v[8:9], s[6:7], v[4:5] op_sel_hi:[1,0,1]
	global_store_dwordx4 v[20:21], v[4:7], off offset:128
	v_lshl_add_u64 v[8:9], v[28:29], 0, v[44:45]
	global_load_dwordx4 v[8:11], v[8:9], off
	s_waitcnt vmcnt(0)
	v_pk_mul_f32 v[2:3], v[2:3], v[10:11]
	global_load_dwordx4 v[4:7], v[26:27], off offset:192
	v_pk_mul_f32 v[0:1], v[0:1], v[8:9]
	s_waitcnt vmcnt(0)
	v_pk_fma_f32 v[2:3], v[6:7], s[6:7], v[2:3] op_sel_hi:[1,0,1]
	v_pk_fma_f32 v[0:1], v[4:5], s[6:7], v[0:1] op_sel_hi:[1,0,1]
	global_store_dwordx4 v[20:21], v[0:3], off offset:192
	s_branch .LBB1_79

.LBB1_88:
	v_readlane_b32 s4, v242, 0
	s_lshl_b32 s5, s2, 3
	s_and_b32 s6, s4, 7
	s_or_b32 s5, s6, s5
	s_mul_i32 s5, s5, s55
	s_ashr_i32 s4, s4, 3
	s_add_i32 s4, s5, s4
	s_cmpk_gt_i32 s4, 0x57f
	s_mov_b64 s[30:31], -1
	s_cbranch_scc1 .LBB1_87
	s_ashr_i32 s5, s4, 31
	s_lshr_b32 s5, s5, 26
	s_add_i32 s5, s4, s5
	s_lshr_b32 s6, s5, 3
	s_andn2_b32 s5, s5, 63
	s_sub_i32 s4, s4, s5
	s_ashr_i32 s5, s4, 31
	s_lshr_b32 s5, s5, 29
	s_add_i32 s7, s4, s5
	s_and_b32 s5, s7, 0x7fffff8
	s_and_b32 s6, s6, 0x1ffffff8
	s_sub_i32 s4, s4, s5
	v_mov_b32_e32 v90, v162
	s_add_i32 s5, s4, s6
	s_load_dwordx16 s[40:55], s[0:1], 0x140
	s_mulk_i32 s5, 0x60
	v_ashrrev_i32_e32 v38, 3, v90
	v_add_u32_e32 v0, s5, v38
	v_ashrrev_i32_e32 v1, 31, v0
	v_lshlrev_b64 v[0:1], 11, v[0:1]
	s_lshl_b32 s4, s7, 4
	s_waitcnt lgkmcnt(0)
	v_lshl_add_u64 v[0:1], s[46:47], 0, v[0:1]
	v_lshlrev_b32_e32 v2, 4, v90
	s_load_dwordx16 s[40:55], s[0:1], 0xc0
	s_and_b32 s4, s4, 0xffffff80
	v_and_b32_e32 v128, 0x70, v2
	v_lshl_add_u64 v[76:77], v[0:1], 0, v[128:129]
	v_add_u32_e32 v0, s4, v38
	v_ashrrev_i32_e32 v1, 31, v0
	v_lshlrev_b64 v[0:1], 11, v[0:1]
	s_waitcnt lgkmcnt(0)
	v_lshl_add_u64 v[0:1], s[46:47], 0, v[0:1]
	s_mov_b32 s6, 0x10000
	v_lshl_add_u64 v[78:79], v[0:1], 0, v[128:129]
	v_add_co_u32_e32 v0, vcc, s6, v76
	s_mov_b32 s7, 0x30000
	s_nop 0
	v_addc_co_u32_e32 v1, vcc, 0, v77, vcc
	v_add_co_u32_e32 v30, vcc, s6, v78
	s_mov_b32 s6, 0x20000
	s_nop 0
	v_addc_co_u32_e32 v31, vcc, 0, v79, vcc
	v_add_co_u32_e32 v32, vcc, s6, v78
	s_nop 0
	v_addc_co_u32_e32 v33, vcc, 0, v79, vcc
	v_add_co_u32_e32 v34, vcc, s7, v78
	s_nop 0
	v_addc_co_u32_e32 v35, vcc, 0, v79, vcc
	v_add_co_u32_e32 v36, vcc, s6, v76
	v_addc_co_u32_e32 v37, vcc, 0, v77, vcc
	s_barrier
	v_ashrrev_i32_e32 v1, 7, v90
	s_movk_i32 s8, 0x90
	v_and_b32_e32 v92, 15, v90
	v_mul_lo_u32 v31, v38, s8
	v_mul_lo_u32 v93, v1, 48
	v_bfe_u32 v91, v90, 4, 2
	v_and_b32_e32 v30, 0x4f, v90
	v_add3_u32 v94, v128, v31, 16
	v_or_b32_e32 v31, v93, v92
	v_mov_b32_e32 v0, 0
	v_lshl_add_u32 v1, v91, 4, 16
	v_mul_u32_u24_e32 v30, 0x90, v30
	v_mul_lo_u32 v31, v31, s8
	s_mov_b64 s[8:9], 0x10000
	s_mov_b64 s[10:11], 0x20000
	s_mov_b64 s[12:13], 0x30000
	s_mov_b32 s7, 0
	s_movk_i32 s6, 0x80
	v_add_u32_e32 v95, 0xd800, v94
	v_add_u32_e32 v96, v1, v31
	v_lshl_add_u64 v[80:81], v[78:79], 0, s[8:9]
	v_lshl_add_u64 v[82:83], v[78:79], 0, s[10:11]
	v_lshl_add_u64 v[84:85], v[78:79], 0, s[12:13]
	v_lshl_add_u64 v[86:87], v[76:77], 0, s[8:9]
	v_lshl_add_u64 v[88:89], v[76:77], 0, s[10:11]
	v_add_u32_e32 v97, v1, v30
	v_mov_b32_e32 v1, v0
	v_mov_b32_e32 v30, v0
	v_mov_b32_e32 v31, v0
	v_mov_b32_e32 v32, v0
	v_mov_b32_e32 v33, v0
	v_mov_b32_e32 v34, v0
	v_mov_b32_e32 v35, v0
	v_mov_b32_e32 v36, v0
	v_mov_b32_e32 v37, v0
	v_mov_b32_e32 v38, v0
	v_mov_b32_e32 v39, v0
	v_mov_b32_e32 v40, v0
	v_mov_b32_e32 v41, v0
	v_mov_b32_e32 v42, v0
	v_mov_b32_e32 v43, v0
	v_mov_b32_e32 v72, v0
	v_mov_b32_e32 v73, v0
	v_mov_b32_e32 v74, v0
	v_mov_b32_e32 v75, v0
	s_waitcnt vmcnt(12)
	s_waitcnt vmcnt(11)
	s_waitcnt vmcnt(10)
	s_waitcnt vmcnt(9)
	s_waitcnt vmcnt(8)
	s_waitcnt vmcnt(7)
	v_mov_b32_e32 v2, v0
	v_mov_b32_e32 v3, v0
	v_mov_b32_e32 v4, v0
	v_mov_b32_e32 v5, v0
	v_mov_b32_e32 v6, v0
	v_mov_b32_e32 v7, v0
	v_mov_b32_e32 v8, v0
	v_mov_b32_e32 v9, v0
	v_mov_b32_e32 v10, v0
	v_mov_b32_e32 v11, v0
	v_mov_b32_e32 v12, v0
	v_mov_b32_e32 v13, v0
	v_mov_b32_e32 v14, v0
	v_mov_b32_e32 v15, v0
	v_mov_b32_e32 v16, v0
	v_mov_b32_e32 v17, v0
	v_mov_b32_e32 v18, v0
	v_mov_b32_e32 v19, v0
	v_mov_b32_e32 v20, v0
	v_mov_b32_e32 v21, v0
	v_mov_b32_e32 v22, v0
	v_mov_b32_e32 v23, v0
	v_mov_b32_e32 v24, v0
	v_mov_b32_e32 v25, v0
	v_mov_b32_e32 v26, v0
	v_mov_b32_e32 v27, v0
	v_mov_b32_e32 v28, v0
	v_mov_b32_e32 v29, v0
	s_waitcnt lgkmcnt(0)
	s_barrier
	v_and_b32_e32 v204, 15, v168
	v_lshrrev_b32_e32 v205, 4, v168
	v_bfe_u32 v206, v168, 1, 3
	v_xor_b32_e32 v205, v205, v206
	v_lshlrev_b32_e32 v205, 4, v205
	v_readfirstlane_b32 s19, v162
	v_readfirstlane_b32 s8, v76
	v_readfirstlane_b32 s9, v77
	v_readfirstlane_b32 s10, v78
	v_readfirstlane_b32 s11, v79
	s_lshr_b32 s19, s19, 6
	s_lshr_b32 s16, s19, 1
	s_and_b32 s17, s19, 1
	s_mul_i32 s16, s16, 48
	v_add_u32_e32 v206, s16, v204
	v_lshl_add_u32 v232, v206, 7, v205
	v_xor_b32_e32 v233, 64, v232
	v_add_u32_e32 v232, 16, v232
	v_add_u32_e32 v233, 16, v233
	v_lshl_add_u32 v206, s17, 6, v204
	v_lshl_add_u32 v234, v206, 7, v205
	v_xor_b32_e32 v235, 64, v234
	v_add_u32_e32 v234, 0x3010, v234
	v_add_u32_e32 v235, 0x3010, v235
	v_lshrrev_b32_e32 v206, 3, v168
	v_and_b32_e32 v207, 7, v168
	v_lshrrev_b32_e32 v204, 1, v206
	v_xor_b32_e32 v207, v207, v204
	v_lshlrev_b32_e32 v207, 4, v207
	v_lshl_add_u32 v236, v206, 11, v207
	v_xor_b32_e32 v237, 64, v236
	s_and_b32 s17, s19, 1
	s_cmp_eq_u32 s17, 0
	s_cselect_b64 vcc, -1, 0
	s_nop 3
	v_cndmask_b32_e32 v238, v237, v236, vcc
	v_cndmask_b32_e32 v239, v236, v237, vcc
	s_mul_i32 s16, s19, 0x8000
	s_add_u32 s8, s8, s16
	s_addc_u32 s9, s9, 0
	s_mul_i32 s16, s19, 0xc000
	s_add_u32 s10, s10, s16
	s_addc_u32 s11, s11, 0
	s_mul_i32 s16, s19, 0xc00
	s_lshl_b32 s17, s19, 12
	s_add_i32 m0, s16, 0x10
	s_nop 0
	global_load_lds_dwordx4 v238, s[8:9]
	s_add_i32 m0, s16, 0x410
	s_add_u32 s12, s8, 0x4000
	s_addc_u32 s13, s9, 0
	global_load_lds_dwordx4 v239, s[12:13]
	s_add_i32 m0, s16, 0x810
	s_add_u32 s12, s8, 0x8000
	s_addc_u32 s13, s9, 0
	global_load_lds_dwordx4 v238, s[12:13]
	s_add_i32 m0, s17, 0x3010
	s_nop 0
	global_load_lds_dwordx4 v236, s[10:11]
	s_add_i32 m0, s17, 0x3410
	s_add_u32 s12, s10, 0x4000
	s_addc_u32 s13, s11, 0
	global_load_lds_dwordx4 v237, s[12:13]
	s_add_i32 m0, s17, 0x3810
	s_add_u32 s12, s10, 0x8000
	s_addc_u32 s13, s11, 0
	global_load_lds_dwordx4 v236, s[12:13]
	s_add_i32 m0, s17, 0x3c10
	s_add_u32 s12, s10, 0xc000
	s_addc_u32 s13, s11, 0
	global_load_lds_dwordx4 v237, s[12:13]
	s_mov_b32 s18, 0
	s_waitcnt vmcnt(0)
	s_barrier
	s_setprio 1
.LBB1_90:
	s_lshl_b32 s19, s18, 8
	s_add_i32 s19, s19, 0x80
	s_min_u32 s19, s19, 0x780
	s_add_u32 s40, s8, s19
	s_addc_u32 s41, s9, 0
	s_add_u32 s42, s10, s19
	s_addc_u32 s43, s11, 0
	ds_read_b128 v[142:145], v234 offset:0
	ds_read_b128 v[146:149], v234 offset:2048
	ds_read_b128 v[150:153], v234 offset:4096
	ds_read_b128 v[154:157], v234 offset:6144
	ds_read_b128 v[130:133], v232 offset:0
	ds_read_b128 v[134:137], v232 offset:2048
	ds_read_b128 v[138:141], v232 offset:4096
	ds_read_b128 v[216:219], v235 offset:0
	ds_read_b128 v[220:223], v235 offset:2048
	ds_read_b128 v[224:227], v235 offset:4096
	ds_read_b128 v[228:231], v235 offset:6144
	ds_read_b128 v[188:191], v233 offset:0
	ds_read_b128 v[192:195], v233 offset:2048
	ds_read_b128 v[196:199], v233 offset:4096
	s_waitcnt lgkmcnt(9)
	s_add_i32 m0, s16, 0x7010
	s_nop 0
	v_mfma_f32_16x16x32_bf16 v[72:75], v[142:145], v[130:133], v[72:75]
	global_load_lds_dwordx4 v238, s[40:41]
	s_add_i32 m0, s16, 0x7410
	s_add_u32 s12, s40, 0x4000
	s_addc_u32 s13, s41, 0
	v_mfma_f32_16x16x32_bf16 v[40:43], v[146:149], v[130:133], v[40:43]
	global_load_lds_dwordx4 v239, s[12:13]
	v_mfma_f32_16x16x32_bf16 v[36:39], v[150:153], v[130:133], v[36:39]
	v_mfma_f32_16x16x32_bf16 v[32:35], v[154:157], v[130:133], v[32:35]
	s_waitcnt lgkmcnt(8)
	s_add_i32 m0, s16, 0x7810
	s_add_u32 s12, s40, 0x8000
	s_addc_u32 s13, s41, 0
	v_mfma_f32_16x16x32_bf16 v[28:31], v[142:145], v[134:137], v[28:31]
	v_mfma_f32_16x16x32_bf16 v[24:27], v[146:149], v[134:137], v[24:27]
	global_load_lds_dwordx4 v238, s[12:13]
	v_mfma_f32_16x16x32_bf16 v[20:23], v[150:153], v[134:137], v[20:23]
	v_mfma_f32_16x16x32_bf16 v[16:19], v[154:157], v[134:137], v[16:19]
	s_waitcnt lgkmcnt(7)
	s_add_i32 m0, s17, 0xa010
	s_nop 0
	v_mfma_f32_16x16x32_bf16 v[12:15], v[142:145], v[138:141], v[12:15]
	v_mfma_f32_16x16x32_bf16 v[8:11], v[146:149], v[138:141], v[8:11]
	global_load_lds_dwordx4 v236, s[42:43]
	v_mfma_f32_16x16x32_bf16 v[4:7], v[150:153], v[138:141], v[4:7]
	v_mfma_f32_16x16x32_bf16 v[0:3], v[154:157], v[138:141], v[0:3]
	s_waitcnt lgkmcnt(2)
	s_add_i32 m0, s17, 0xa410
	s_add_u32 s12, s42, 0x4000
	s_addc_u32 s13, s43, 0
	v_mfma_f32_16x16x32_bf16 v[72:75], v[216:219], v[188:191], v[72:75]
	v_mfma_f32_16x16x32_bf16 v[40:43], v[220:223], v[188:191], v[40:43]
	global_load_lds_dwordx4 v237, s[12:13]
	v_mfma_f32_16x16x32_bf16 v[36:39], v[224:227], v[188:191], v[36:39]
	v_mfma_f32_16x16x32_bf16 v[32:35], v[228:231], v[188:191], v[32:35]
	s_waitcnt lgkmcnt(1)
	s_add_i32 m0, s17, 0xa810
	s_add_u32 s12, s42, 0x8000
	s_addc_u32 s13, s43, 0
	v_mfma_f32_16x16x32_bf16 v[28:31], v[216:219], v[192:195], v[28:31]
	v_mfma_f32_16x16x32_bf16 v[24:27], v[220:223], v[192:195], v[24:27]
	global_load_lds_dwordx4 v236, s[12:13]
	v_mfma_f32_16x16x32_bf16 v[20:23], v[224:227], v[192:195], v[20:23]
	v_mfma_f32_16x16x32_bf16 v[16:19], v[228:231], v[192:195], v[16:19]
	s_waitcnt lgkmcnt(0)
	s_add_i32 m0, s17, 0xac10
	s_add_u32 s12, s42, 0xc000
	s_addc_u32 s13, s43, 0
	v_mfma_f32_16x16x32_bf16 v[12:15], v[216:219], v[196:199], v[12:15]
	v_mfma_f32_16x16x32_bf16 v[8:11], v[220:223], v[196:199], v[8:11]
	global_load_lds_dwordx4 v237, s[12:13]
	v_mfma_f32_16x16x32_bf16 v[4:7], v[224:227], v[196:199], v[4:7]
	v_mfma_f32_16x16x32_bf16 v[0:3], v[228:231], v[196:199], v[0:3]
	s_waitcnt vmcnt(0)
	s_barrier
	s_lshl_b32 s19, s18, 8
	s_add_i32 s19, s19, 0x100
	s_min_u32 s19, s19, 0x780
	s_add_u32 s40, s8, s19
	s_addc_u32 s41, s9, 0
	s_add_u32 s42, s10, s19
	s_addc_u32 s43, s11, 0
	ds_read_b128 v[142:145], v234 offset:28672
	ds_read_b128 v[146:149], v234 offset:30720
	ds_read_b128 v[150:153], v234 offset:32768
	ds_read_b128 v[154:157], v234 offset:34816
	ds_read_b128 v[130:133], v232 offset:28672
	ds_read_b128 v[134:137], v232 offset:30720
	ds_read_b128 v[138:141], v232 offset:32768
	ds_read_b128 v[216:219], v235 offset:28672
	ds_read_b128 v[220:223], v235 offset:30720
	ds_read_b128 v[224:227], v235 offset:32768
	ds_read_b128 v[228:231], v235 offset:34816
	ds_read_b128 v[188:191], v233 offset:28672
	ds_read_b128 v[192:195], v233 offset:30720
	ds_read_b128 v[196:199], v233 offset:32768
	s_waitcnt lgkmcnt(9)
	s_add_i32 m0, s16, 0x10
	s_nop 0
	v_mfma_f32_16x16x32_bf16 v[72:75], v[142:145], v[130:133], v[72:75]
	global_load_lds_dwordx4 v238, s[40:41]
	s_add_i32 m0, s16, 0x410
	s_add_u32 s12, s40, 0x4000
	s_addc_u32 s13, s41, 0
	v_mfma_f32_16x16x32_bf16 v[40:43], v[146:149], v[130:133], v[40:43]
	global_load_lds_dwordx4 v239, s[12:13]
	v_mfma_f32_16x16x32_bf16 v[36:39], v[150:153], v[130:133], v[36:39]
	v_mfma_f32_16x16x32_bf16 v[32:35], v[154:157], v[130:133], v[32:35]
	s_waitcnt lgkmcnt(8)
	s_add_i32 m0, s16, 0x810
	s_add_u32 s12, s40, 0x8000
	s_addc_u32 s13, s41, 0
	v_mfma_f32_16x16x32_bf16 v[28:31], v[142:145], v[134:137], v[28:31]
	v_mfma_f32_16x16x32_bf16 v[24:27], v[146:149], v[134:137], v[24:27]
	global_load_lds_dwordx4 v238, s[12:13]
	v_mfma_f32_16x16x32_bf16 v[20:23], v[150:153], v[134:137], v[20:23]
	v_mfma_f32_16x16x32_bf16 v[16:19], v[154:157], v[134:137], v[16:19]
	s_waitcnt lgkmcnt(7)
	s_add_i32 m0, s17, 0x3010
	s_nop 0
	v_mfma_f32_16x16x32_bf16 v[12:15], v[142:145], v[138:141], v[12:15]
	v_mfma_f32_16x16x32_bf16 v[8:11], v[146:149], v[138:141], v[8:11]
	global_load_lds_dwordx4 v236, s[42:43]
	v_mfma_f32_16x16x32_bf16 v[4:7], v[150:153], v[138:141], v[4:7]
	v_mfma_f32_16x16x32_bf16 v[0:3], v[154:157], v[138:141], v[0:3]
	s_waitcnt lgkmcnt(2)
	s_add_i32 m0, s17, 0x3410
	s_add_u32 s12, s42, 0x4000
	s_addc_u32 s13, s43, 0
	v_mfma_f32_16x16x32_bf16 v[72:75], v[216:219], v[188:191], v[72:75]
	v_mfma_f32_16x16x32_bf16 v[40:43], v[220:223], v[188:191], v[40:43]
	global_load_lds_dwordx4 v237, s[12:13]
	v_mfma_f32_16x16x32_bf16 v[36:39], v[224:227], v[188:191], v[36:39]
	v_mfma_f32_16x16x32_bf16 v[32:35], v[228:231], v[188:191], v[32:35]
	s_waitcnt lgkmcnt(1)
	s_add_i32 m0, s17, 0x3810
	s_add_u32 s12, s42, 0x8000
	s_addc_u32 s13, s43, 0
	v_mfma_f32_16x16x32_bf16 v[28:31], v[216:219], v[192:195], v[28:31]
	v_mfma_f32_16x16x32_bf16 v[24:27], v[220:223], v[192:195], v[24:27]
	global_load_lds_dwordx4 v236, s[12:13]
	v_mfma_f32_16x16x32_bf16 v[20:23], v[224:227], v[192:195], v[20:23]
	v_mfma_f32_16x16x32_bf16 v[16:19], v[228:231], v[192:195], v[16:19]
	s_waitcnt lgkmcnt(0)
	s_add_i32 m0, s17, 0x3c10
	s_add_u32 s12, s42, 0xc000
	s_addc_u32 s13, s43, 0
	v_mfma_f32_16x16x32_bf16 v[12:15], v[216:219], v[196:199], v[12:15]
	v_mfma_f32_16x16x32_bf16 v[8:11], v[220:223], v[196:199], v[8:11]
	global_load_lds_dwordx4 v237, s[12:13]
	v_mfma_f32_16x16x32_bf16 v[4:7], v[224:227], v[196:199], v[4:7]
	v_mfma_f32_16x16x32_bf16 v[0:3], v[228:231], v[196:199], v[0:3]
	s_waitcnt vmcnt(0)
	s_barrier
	s_add_i32 s18, s18, 1
	s_cmp_eq_u32 s18, 8
	s_cbranch_scc0 .LBB1_90
	s_setprio 0
	s_waitcnt vmcnt(6)
	v_or_b32_e32 v45, s5, v92
	s_waitcnt vmcnt(4)
	v_add_u32_e32 v52, v45, v93
	v_and_b32_e32 v44, 64, v90
	v_lshlrev_b32_e32 v45, 2, v91
	v_ashrrev_i32_e32 v53, 31, v52
	s_waitcnt vmcnt(2)
	v_or3_b32 v60, v45, v44, s4
	v_lshlrev_b64 v[44:45], 14, v[52:53]
	v_lshl_add_u64 v[44:45], s[76:77], 0, v[44:45]
	s_mov_b64 s[4:5], 0x3000
	v_ashrrev_i32_e32 v61, 31, v60
	v_lshl_add_u64 v[58:59], v[44:45], 0, s[4:5]
	v_lshlrev_b64 v[46:47], 1, v[60:61]
	v_lshl_add_u64 v[44:45], v[58:59], 0, v[46:47]
	global_load_dwordx2 v[44:45], v[44:45], off
	v_readlane_b32 s6, v241, 34
	v_lshlrev_b64 v[48:49], 2, v[60:61]
	v_readlane_b32 s7, v241, 35
	s_load_dwordx16 s[40:55], s[0:1], 0x140
	s_add_i32 s2, s2, 1
	s_mov_b64 s[30:31], 0
	s_waitcnt lgkmcnt(0)
	v_readlane_b32 s55, v241, 23
	s_waitcnt vmcnt(0)
	v_lshlrev_b32_e32 v50, 16, v44
	v_and_b32_e32 v51, 0xffff0000, v44
	v_lshlrev_b32_e32 v62, 16, v45
	v_and_b32_e32 v63, 0xffff0000, v45
	v_lshl_add_u64 v[44:45], s[6:7], 0, v[48:49]
	global_load_dwordx4 v[54:57], v[44:45], off
	s_waitcnt vmcnt(0)
	v_pk_add_f32 v[56:57], v[56:57], v[62:63]
	v_pk_add_f32 v[50:51], v[54:55], v[50:51]
	v_mul_f32_e32 v54, 0xbfb8aa3b, v56
	v_exp_f32_e32 v54, v54
	v_mul_f32_e32 v50, 0xbfb8aa3b, v50
	v_mul_f32_e32 v51, 0xbfb8aa3b, v51
	v_exp_f32_e32 v50, v50
	v_add_f32_e32 v54, 1.0, v54
	v_rcp_f32_e32 v56, v54
	v_mul_f32_e32 v54, 0xbfb8aa3b, v57
	v_exp_f32_e32 v54, v54
	v_exp_f32_e32 v51, v51
	v_add_f32_e32 v50, 1.0, v50
	v_rcp_f32_e32 v50, v50
	v_add_f32_e32 v54, 1.0, v54
	v_rcp_f32_e32 v57, v54
	v_lshlrev_b64 v[54:55], 12, v[52:53]
	v_lshl_add_u64 v[54:55], s[72:73], 0, v[54:55]
	v_lshl_add_u64 v[54:55], v[54:55], 0, v[48:49]
	global_load_dwordx4 v[62:65], v[54:55], off
	v_add_f32_e32 v51, 1.0, v51
	v_rcp_f32_e32 v51, v51
	s_waitcnt vmcnt(0)
	v_pk_fma_f32 v[56:57], v[74:75], v[56:57], v[64:65]
	v_pk_fma_f32 v[50:51], v[72:73], v[50:51], v[62:63]
	s_nop 0
	v_cvt_pk_bf16_f32 v50, v50, v51
	v_cvt_pk_bf16_f32 v51, v56, v57
	v_lshlrev_b64 v[56:57], 11, v[52:53]
	v_lshl_add_u64 v[56:57], s[50:51], 0, v[56:57]
	v_lshl_add_u64 v[56:57], v[56:57], 0, v[46:47]
	global_store_dwordx2 v[56:57], v[50:51], off
	v_or_b32_e32 v50, 16, v60
	v_ashrrev_i32_e32 v51, 31, v50
	v_lshlrev_b64 v[50:51], 1, v[50:51]
	v_lshl_add_u64 v[62:63], v[58:59], 0, v[50:51]
	global_load_dwordx2 v[62:63], v[62:63], off
	s_waitcnt vmcnt(0)
	v_lshlrev_b32_e32 v66, 16, v62
	v_and_b32_e32 v67, 0xffff0000, v62
	v_lshlrev_b32_e32 v68, 16, v63
	v_and_b32_e32 v69, 0xffff0000, v63
	global_load_dwordx4 v[62:65], v[44:45], off offset:64
	s_waitcnt vmcnt(0)
	v_pk_add_f32 v[62:63], v[62:63], v[66:67]
	s_nop 0
	v_mul_f32_e32 v53, 0xbfb8aa3b, v62
	v_exp_f32_e32 v53, v53
	v_pk_add_f32 v[64:65], v[64:65], v[68:69]
	v_add_f32_e32 v53, 1.0, v53
	v_rcp_f32_e32 v66, v53
	v_mul_f32_e32 v53, 0xbfb8aa3b, v63
	v_exp_f32_e32 v53, v53
	s_nop 0
	v_add_f32_e32 v53, 1.0, v53
	v_rcp_f32_e32 v67, v53
	v_mul_f32_e32 v53, 0xbfb8aa3b, v64
	v_exp_f32_e32 v53, v53
	s_nop 0
	v_add_f32_e32 v53, 1.0, v53
	v_rcp_f32_e32 v68, v53
	v_mul_f32_e32 v53, 0xbfb8aa3b, v65
	global_load_dwordx4 v[62:65], v[54:55], off offset:64
	v_exp_f32_e32 v53, v53
	s_waitcnt vmcnt(0)
	v_pk_fma_f32 v[40:41], v[40:41], v[66:67], v[62:63]
	v_add_f32_e32 v53, 1.0, v53
	v_rcp_f32_e32 v69, v53
	v_cvt_pk_bf16_f32 v40, v40, v41
	v_pk_fma_f32 v[42:43], v[42:43], v[68:69], v[64:65]
	s_nop 0
	v_cvt_pk_bf16_f32 v41, v42, v43
	global_store_dwordx2 v[56:57], v[40:41], off offset:32
	v_or_b32_e32 v40, 32, v60
	v_ashrrev_i32_e32 v41, 31, v40
	v_lshlrev_b64 v[40:41], 1, v[40:41]
	v_lshl_add_u64 v[42:43], v[58:59], 0, v[40:41]
	global_load_dwordx2 v[42:43], v[42:43], off
	s_waitcnt vmcnt(0)
	v_lshlrev_b32_e32 v66, 16, v42
	global_load_dwordx4 v[62:65], v[44:45], off offset:128
	v_and_b32_e32 v67, 0xffff0000, v42
	v_lshlrev_b32_e32 v42, 16, v43
	v_and_b32_e32 v43, 0xffff0000, v43
	s_waitcnt vmcnt(0)
	v_pk_add_f32 v[62:63], v[62:63], v[66:67]
	s_nop 0
	v_mul_f32_e32 v53, 0xbfb8aa3b, v62
	v_exp_f32_e32 v53, v53
	v_pk_add_f32 v[42:43], v[64:65], v[42:43]
	v_add_f32_e32 v53, 1.0, v53
	v_rcp_f32_e32 v66, v53
	v_mul_f32_e32 v53, 0xbfb8aa3b, v63
	global_load_dwordx4 v[62:65], v[54:55], off offset:128
	v_mul_f32_e32 v42, 0xbfb8aa3b, v42
	v_mul_f32_e32 v43, 0xbfb8aa3b, v43
	v_exp_f32_e32 v53, v53
	v_exp_f32_e32 v42, v42
	v_exp_f32_e32 v43, v43
	v_add_f32_e32 v53, 1.0, v53
	v_add_f32_e32 v42, 1.0, v42
	v_add_f32_e32 v43, 1.0, v43
	v_rcp_f32_e32 v67, v53
	v_rcp_f32_e32 v42, v42
	v_rcp_f32_e32 v43, v43
	s_waitcnt vmcnt(0)
	v_pk_fma_f32 v[36:37], v[36:37], v[66:67], v[62:63]
	v_pk_fma_f32 v[38:39], v[38:39], v[42:43], v[64:65]
	v_cvt_pk_bf16_f32 v36, v36, v37
	v_cvt_pk_bf16_f32 v37, v38, v39
	global_store_dwordx2 v[56:57], v[36:37], off offset:64
	v_or_b32_e32 v36, 48, v60
	v_ashrrev_i32_e32 v37, 31, v36
	v_lshlrev_b64 v[36:37], 1, v[36:37]
	v_lshl_add_u64 v[38:39], v[58:59], 0, v[36:37]
	global_load_dwordx2 v[38:39], v[38:39], off
	s_waitcnt vmcnt(0)
	v_lshlrev_b32_e32 v42, 16, v38
	global_load_dwordx4 v[58:61], v[44:45], off offset:192
	v_and_b32_e32 v43, 0xffff0000, v38
	v_lshlrev_b32_e32 v38, 16, v39
	v_and_b32_e32 v39, 0xffff0000, v39
	s_waitcnt vmcnt(0)
	v_pk_add_f32 v[38:39], v[60:61], v[38:39]
	v_pk_add_f32 v[42:43], v[58:59], v[42:43]
	global_load_dwordx4 v[58:61], v[54:55], off offset:192
	v_mul_f32_e32 v42, 0xbfb8aa3b, v42
	v_mul_f32_e32 v43, 0xbfb8aa3b, v43
	v_mul_f32_e32 v38, 0xbfb8aa3b, v38
	v_mul_f32_e32 v39, 0xbfb8aa3b, v39
	v_exp_f32_e32 v42, v42
	v_exp_f32_e32 v43, v43
	v_exp_f32_e32 v38, v38
	v_exp_f32_e32 v39, v39
	v_add_f32_e32 v42, 1.0, v42
	v_add_f32_e32 v43, 1.0, v43
	v_add_f32_e32 v38, 1.0, v38
	v_add_f32_e32 v39, 1.0, v39
	v_rcp_f32_e32 v42, v42
	v_rcp_f32_e32 v43, v43
	v_rcp_f32_e32 v38, v38
	v_rcp_f32_e32 v39, v39
	s_waitcnt vmcnt(0)
	v_pk_fma_f32 v[32:33], v[32:33], v[42:43], v[58:59]
	v_pk_fma_f32 v[34:35], v[34:35], v[38:39], v[60:61]
	v_add_u32_e32 v38, 16, v52
	v_cvt_pk_bf16_f32 v32, v32, v33
	v_cvt_pk_bf16_f32 v33, v34, v35
	v_ashrrev_i32_e32 v39, 31, v38
	global_store_dwordx2 v[56:57], v[32:33], off offset:96
	v_lshlrev_b64 v[32:33], 14, v[38:39]
	v_lshl_add_u64 v[32:33], s[76:77], 0, v[32:33]
	v_lshl_add_u64 v[32:33], v[32:33], 0, s[4:5]
	v_lshl_add_u64 v[34:35], v[32:33], 0, v[46:47]
	global_load_dwordx2 v[34:35], v[34:35], off
	s_waitcnt vmcnt(0)
	v_lshlrev_b32_e32 v42, 16, v34
	global_load_dwordx4 v[54:57], v[44:45], off
	v_and_b32_e32 v43, 0xffff0000, v34
	v_lshlrev_b32_e32 v34, 16, v35
	v_and_b32_e32 v35, 0xffff0000, v35
	s_waitcnt vmcnt(0)
	v_pk_add_f32 v[34:35], v[56:57], v[34:35]
	s_nop 0
	v_mul_f32_e32 v34, 0xbfb8aa3b, v34
	v_exp_f32_e32 v34, v34
	v_pk_add_f32 v[42:43], v[54:55], v[42:43]
	v_add_f32_e32 v34, 1.0, v34
	v_rcp_f32_e32 v58, v34
	v_mul_f32_e32 v34, 0xbfb8aa3b, v35
	v_exp_f32_e32 v34, v34
	v_mul_f32_e32 v42, 0xbfb8aa3b, v42
	v_mul_f32_e32 v43, 0xbfb8aa3b, v43
	v_exp_f32_e32 v42, v42
	v_add_f32_e32 v34, 1.0, v34
	v_rcp_f32_e32 v59, v34
	v_lshlrev_b64 v[34:35], 12, v[38:39]
	v_lshl_add_u64 v[34:35], s[72:73], 0, v[34:35]
	v_lshl_add_u64 v[34:35], v[34:35], 0, v[48:49]
	global_load_dwordx4 v[54:57], v[34:35], off
	v_exp_f32_e32 v43, v43
	v_add_f32_e32 v42, 1.0, v42
	v_rcp_f32_e32 v42, v42
	v_add_f32_e32 v43, 1.0, v43
	v_rcp_f32_e32 v43, v43
	s_waitcnt vmcnt(0)
	v_pk_fma_f32 v[30:31], v[30:31], v[58:59], v[56:57]
	v_pk_fma_f32 v[28:29], v[28:29], v[42:43], v[54:55]
	v_cvt_pk_bf16_f32 v43, v30, v31
	v_cvt_pk_bf16_f32 v42, v28, v29
	v_lshlrev_b64 v[28:29], 11, v[38:39]
	v_lshl_add_u64 v[28:29], s[50:51], 0, v[28:29]
	v_lshl_add_u64 v[28:29], v[28:29], 0, v[46:47]
	global_store_dwordx2 v[28:29], v[42:43], off
	v_lshl_add_u64 v[30:31], v[32:33], 0, v[50:51]
	global_load_dwordx2 v[30:31], v[30:31], off
	s_waitcnt vmcnt(0)
	v_lshlrev_b32_e32 v38, 16, v30
	global_load_dwordx4 v[54:57], v[44:45], off offset:64
	v_and_b32_e32 v39, 0xffff0000, v30
	v_lshlrev_b32_e32 v30, 16, v31
	v_and_b32_e32 v31, 0xffff0000, v31
	s_waitcnt vmcnt(0)
	v_pk_add_f32 v[30:31], v[56:57], v[30:31]
	v_pk_add_f32 v[38:39], v[54:55], v[38:39]
	global_load_dwordx4 v[54:57], v[34:35], off offset:64
	v_mul_f32_e32 v38, 0xbfb8aa3b, v38
	v_mul_f32_e32 v39, 0xbfb8aa3b, v39
	v_mul_f32_e32 v30, 0xbfb8aa3b, v30
	v_mul_f32_e32 v31, 0xbfb8aa3b, v31
	v_exp_f32_e32 v38, v38
	v_exp_f32_e32 v39, v39
	v_exp_f32_e32 v30, v30
	v_exp_f32_e32 v31, v31
	v_add_f32_e32 v38, 1.0, v38
	v_add_f32_e32 v39, 1.0, v39
	v_add_f32_e32 v30, 1.0, v30
	v_add_f32_e32 v31, 1.0, v31
	v_rcp_f32_e32 v38, v38
	v_rcp_f32_e32 v39, v39
	v_rcp_f32_e32 v30, v30
	v_rcp_f32_e32 v31, v31
	s_waitcnt vmcnt(0)
	v_pk_fma_f32 v[24:25], v[24:25], v[38:39], v[54:55]
	v_pk_fma_f32 v[26:27], v[26:27], v[30:31], v[56:57]
	v_cvt_pk_bf16_f32 v24, v24, v25
	v_cvt_pk_bf16_f32 v25, v26, v27
	global_store_dwordx2 v[28:29], v[24:25], off offset:32
	v_lshl_add_u64 v[24:25], v[32:33], 0, v[40:41]
	global_load_dwordx2 v[24:25], v[24:25], off
	s_waitcnt vmcnt(0)
	v_lshlrev_b32_e32 v30, 16, v24
	v_and_b32_e32 v31, 0xffff0000, v24
	v_lshlrev_b32_e32 v38, 16, v25
	v_and_b32_e32 v39, 0xffff0000, v25
	global_load_dwordx4 v[24:27], v[44:45], off offset:128
	s_waitcnt vmcnt(0)
	v_pk_add_f32 v[24:25], v[24:25], v[30:31]
	s_nop 0
	v_mul_f32_e32 v24, 0xbfb8aa3b, v24
	v_exp_f32_e32 v24, v24
	v_pk_add_f32 v[26:27], v[26:27], v[38:39]
	v_add_f32_e32 v24, 1.0, v24
	v_rcp_f32_e32 v30, v24
	v_mul_f32_e32 v24, 0xbfb8aa3b, v25
	v_exp_f32_e32 v24, v24
	s_nop 0
	v_add_f32_e32 v24, 1.0, v24
	v_rcp_f32_e32 v31, v24
	v_mul_f32_e32 v24, 0xbfb8aa3b, v26
	v_exp_f32_e32 v24, v24
	s_nop 0
	v_add_f32_e32 v24, 1.0, v24
	v_rcp_f32_e32 v38, v24
	v_mul_f32_e32 v24, 0xbfb8aa3b, v27
	v_exp_f32_e32 v24, v24
	s_nop 0
	v_add_f32_e32 v24, 1.0, v24
	v_rcp_f32_e32 v39, v24
	global_load_dwordx4 v[24:27], v[34:35], off offset:128
	s_waitcnt vmcnt(0)
	v_pk_fma_f32 v[22:23], v[22:23], v[38:39], v[26:27]
	v_pk_fma_f32 v[20:21], v[20:21], v[30:31], v[24:25]
	s_nop 0
	v_cvt_pk_bf16_f32 v20, v20, v21
	v_cvt_pk_bf16_f32 v21, v22, v23
	global_store_dwordx2 v[28:29], v[20:21], off offset:64
	v_lshl_add_u64 v[20:21], v[32:33], 0, v[36:37]
	global_load_dwordx2 v[20:21], v[20:21], off
	s_waitcnt vmcnt(0)
	v_lshlrev_b32_e32 v24, 16, v20
	v_and_b32_e32 v25, 0xffff0000, v20
	v_lshlrev_b32_e32 v26, 16, v21
	v_and_b32_e32 v27, 0xffff0000, v21
	global_load_dwordx4 v[20:23], v[44:45], off offset:192
	s_waitcnt vmcnt(0)
	v_pk_add_f32 v[20:21], v[20:21], v[24:25]
	s_nop 0
	v_mul_f32_e32 v20, 0xbfb8aa3b, v20
	v_exp_f32_e32 v20, v20
	v_pk_add_f32 v[22:23], v[22:23], v[26:27]
	v_add_f32_e32 v20, 1.0, v20
	v_rcp_f32_e32 v24, v20
	v_mul_f32_e32 v20, 0xbfb8aa3b, v21
	v_exp_f32_e32 v20, v20
	s_nop 0
	v_add_f32_e32 v20, 1.0, v20
	v_rcp_f32_e32 v25, v20
	v_mul_f32_e32 v20, 0xbfb8aa3b, v22
	v_exp_f32_e32 v20, v20
	s_nop 0
	v_add_f32_e32 v20, 1.0, v20
	v_rcp_f32_e32 v26, v20
	v_mul_f32_e32 v20, 0xbfb8aa3b, v23
	v_exp_f32_e32 v20, v20
	s_nop 0
	v_add_f32_e32 v20, 1.0, v20
	v_rcp_f32_e32 v27, v20
	global_load_dwordx4 v[20:23], v[34:35], off offset:192
	s_waitcnt vmcnt(0)
	v_pk_fma_f32 v[18:19], v[18:19], v[26:27], v[22:23]
	v_pk_fma_f32 v[16:17], v[16:17], v[24:25], v[20:21]
	v_add_u32_e32 v20, 32, v52
	v_cvt_pk_bf16_f32 v16, v16, v17
	v_cvt_pk_bf16_f32 v17, v18, v19
	v_ashrrev_i32_e32 v21, 31, v20
	global_store_dwordx2 v[28:29], v[16:17], off offset:96
	v_lshlrev_b64 v[16:17], 14, v[20:21]
	v_lshl_add_u64 v[16:17], s[76:77], 0, v[16:17]
	v_lshl_add_u64 v[16:17], v[16:17], 0, s[4:5]
	v_lshl_add_u64 v[18:19], v[16:17], 0, v[46:47]
	global_load_dwordx2 v[18:19], v[18:19], off
	s_waitcnt vmcnt(0)
	v_lshlrev_b32_e32 v26, 16, v18
	global_load_dwordx4 v[22:25], v[44:45], off
	v_and_b32_e32 v27, 0xffff0000, v18
	v_lshlrev_b32_e32 v18, 16, v19
	v_and_b32_e32 v19, 0xffff0000, v19
	s_waitcnt vmcnt(0)
	v_pk_add_f32 v[18:19], v[24:25], v[18:19]
	s_nop 0
	v_mul_f32_e32 v18, 0xbfb8aa3b, v18
	v_exp_f32_e32 v18, v18
	v_pk_add_f32 v[22:23], v[22:23], v[26:27]
	v_add_f32_e32 v18, 1.0, v18
	v_mul_f32_e32 v22, 0xbfb8aa3b, v22
	v_exp_f32_e32 v22, v22
	v_rcp_f32_e32 v28, v18
	v_mul_f32_e32 v18, 0xbfb8aa3b, v19
	v_exp_f32_e32 v18, v18
	v_add_f32_e32 v22, 1.0, v22
	v_rcp_f32_e32 v26, v22
	v_mul_f32_e32 v22, 0xbfb8aa3b, v23
	v_exp_f32_e32 v22, v22
	v_add_f32_e32 v18, 1.0, v18
	v_rcp_f32_e32 v29, v18
	v_lshlrev_b64 v[18:19], 12, v[20:21]
	v_lshl_add_u64 v[18:19], s[72:73], 0, v[18:19]
	v_add_f32_e32 v22, 1.0, v22
	v_lshl_add_u64 v[18:19], v[18:19], 0, v[48:49]
	v_rcp_f32_e32 v27, v22
	global_load_dwordx4 v[22:25], v[18:19], off
	s_waitcnt vmcnt(0)
	v_pk_fma_f32 v[12:13], v[12:13], v[26:27], v[22:23]
	s_nop 0
	v_cvt_pk_bf16_f32 v22, v12, v13
	v_lshlrev_b64 v[12:13], 11, v[20:21]
	v_pk_fma_f32 v[14:15], v[14:15], v[28:29], v[24:25]
	v_lshl_add_u64 v[12:13], s[50:51], 0, v[12:13]
	v_cvt_pk_bf16_f32 v23, v14, v15
	v_lshl_add_u64 v[12:13], v[12:13], 0, v[46:47]
	global_store_dwordx2 v[12:13], v[22:23], off
	v_lshl_add_u64 v[14:15], v[16:17], 0, v[50:51]
	global_load_dwordx2 v[14:15], v[14:15], off
	s_waitcnt vmcnt(0)
	v_lshlrev_b32_e32 v24, 16, v14
	global_load_dwordx4 v[20:23], v[44:45], off offset:64
	v_and_b32_e32 v25, 0xffff0000, v14
	v_lshlrev_b32_e32 v14, 16, v15
	v_and_b32_e32 v15, 0xffff0000, v15
	s_waitcnt vmcnt(0)
	v_pk_add_f32 v[20:21], v[20:21], v[24:25]
	s_nop 0
	v_mul_f32_e32 v20, 0xbfb8aa3b, v20
	v_exp_f32_e32 v20, v20
	v_pk_add_f32 v[14:15], v[22:23], v[14:15]
	v_add_f32_e32 v20, 1.0, v20
	v_rcp_f32_e32 v24, v20
	v_mul_f32_e32 v20, 0xbfb8aa3b, v21
	v_exp_f32_e32 v20, v20
	v_mul_f32_e32 v14, 0xbfb8aa3b, v14
	v_mul_f32_e32 v15, 0xbfb8aa3b, v15
	v_exp_f32_e32 v14, v14
	v_add_f32_e32 v20, 1.0, v20
	v_rcp_f32_e32 v25, v20
	global_load_dwordx4 v[20:23], v[18:19], off offset:64
	v_exp_f32_e32 v15, v15
	v_add_f32_e32 v14, 1.0, v14
	v_rcp_f32_e32 v14, v14
	v_add_f32_e32 v15, 1.0, v15
	v_rcp_f32_e32 v15, v15
	s_waitcnt vmcnt(0)
	v_pk_fma_f32 v[8:9], v[8:9], v[24:25], v[20:21]
	v_pk_fma_f32 v[10:11], v[10:11], v[14:15], v[22:23]
	v_cvt_pk_bf16_f32 v8, v8, v9
	v_cvt_pk_bf16_f32 v9, v10, v11
	global_store_dwordx2 v[12:13], v[8:9], off offset:32
	v_lshl_add_u64 v[8:9], v[16:17], 0, v[40:41]
	global_load_dwordx2 v[8:9], v[8:9], off
	s_waitcnt vmcnt(0)
	v_lshlrev_b32_e32 v14, 16, v8
	v_and_b32_e32 v15, 0xffff0000, v8
	v_lshlrev_b32_e32 v20, 16, v9
	v_and_b32_e32 v21, 0xffff0000, v9
	global_load_dwordx4 v[8:11], v[44:45], off offset:128
	s_waitcnt vmcnt(0)
	v_pk_add_f32 v[8:9], v[8:9], v[14:15]
	s_nop 0
	v_mul_f32_e32 v8, 0xbfb8aa3b, v8
	v_exp_f32_e32 v8, v8
	v_pk_add_f32 v[10:11], v[10:11], v[20:21]
	v_add_f32_e32 v8, 1.0, v8
	v_rcp_f32_e32 v14, v8
	v_mul_f32_e32 v8, 0xbfb8aa3b, v9
	v_exp_f32_e32 v8, v8
	s_nop 0
	v_add_f32_e32 v8, 1.0, v8
	v_rcp_f32_e32 v15, v8
	v_mul_f32_e32 v8, 0xbfb8aa3b, v10
	v_exp_f32_e32 v8, v8
	s_nop 0
	v_add_f32_e32 v8, 1.0, v8
	v_rcp_f32_e32 v20, v8
	v_mul_f32_e32 v8, 0xbfb8aa3b, v11
	v_exp_f32_e32 v8, v8
	s_nop 0
	v_add_f32_e32 v8, 1.0, v8
	v_rcp_f32_e32 v21, v8
	global_load_dwordx4 v[8:11], v[18:19], off offset:128
	s_waitcnt vmcnt(0)
	v_pk_fma_f32 v[6:7], v[6:7], v[20:21], v[10:11]
	v_pk_fma_f32 v[4:5], v[4:5], v[14:15], v[8:9]
	s_nop 0
	v_cvt_pk_bf16_f32 v4, v4, v5
	v_cvt_pk_bf16_f32 v5, v6, v7
	global_store_dwordx2 v[12:13], v[4:5], off offset:64
	v_lshl_add_u64 v[4:5], v[16:17], 0, v[36:37]
	global_load_dwordx2 v[4:5], v[4:5], off
	s_waitcnt vmcnt(0)
	v_lshlrev_b32_e32 v8, 16, v4
	v_and_b32_e32 v9, 0xffff0000, v4
	v_lshlrev_b32_e32 v10, 16, v5
	v_and_b32_e32 v11, 0xffff0000, v5
	global_load_dwordx4 v[4:7], v[44:45], off offset:192
	s_waitcnt vmcnt(0)
	v_pk_add_f32 v[4:5], v[4:5], v[8:9]
	s_nop 0
	v_mul_f32_e32 v4, 0xbfb8aa3b, v4
	v_exp_f32_e32 v4, v4
	v_pk_add_f32 v[6:7], v[6:7], v[10:11]
	v_add_f32_e32 v4, 1.0, v4
	v_rcp_f32_e32 v8, v4
	v_mul_f32_e32 v4, 0xbfb8aa3b, v5
	v_exp_f32_e32 v4, v4
	s_nop 0
	v_add_f32_e32 v4, 1.0, v4
	v_rcp_f32_e32 v9, v4
	v_mul_f32_e32 v4, 0xbfb8aa3b, v6
	v_exp_f32_e32 v4, v4
	s_nop 0
	v_add_f32_e32 v4, 1.0, v4
	v_rcp_f32_e32 v10, v4
	v_mul_f32_e32 v4, 0xbfb8aa3b, v7
	v_exp_f32_e32 v4, v4
	s_nop 0
	v_add_f32_e32 v4, 1.0, v4
	v_rcp_f32_e32 v11, v4
	global_load_dwordx4 v[4:7], v[18:19], off offset:192
	s_waitcnt vmcnt(0)
	v_pk_fma_f32 v[2:3], v[2:3], v[10:11], v[6:7]
	v_pk_fma_f32 v[0:1], v[0:1], v[8:9], v[4:5]
	s_nop 0
	v_cvt_pk_bf16_f32 v0, v0, v1
	v_cvt_pk_bf16_f32 v1, v2, v3
	global_store_dwordx2 v[12:13], v[0:1], off offset:96
	s_branch .LBB1_87

.LBB1_807:
	s_mul_hi_i32 s4, s2, 0x2e8ba2e9
	s_lshr_b32 s5, s4, 31
	s_ashr_i32 s4, s4, 5
	s_add_i32 s4, s4, s5
	s_mul_i32 s5, s4, 0xb0
	v_mov_b32_e32 v90, v162
	s_sub_i32 s5, s2, s5
	s_load_dwordx16 s[40:55], s[0:1], 0x140
	s_mulk_i32 s5, 0x60
	v_ashrrev_i32_e32 v38, 3, v90
	v_add_u32_e32 v0, s5, v38
	v_ashrrev_i32_e32 v1, 31, v0
	v_lshlrev_b64 v[0:1], 11, v[0:1]
	s_waitcnt lgkmcnt(0)
	v_lshl_add_u64 v[0:1], s[48:49], 0, v[0:1]
	v_lshlrev_b32_e32 v2, 4, v90
	s_load_dwordx16 s[40:55], s[0:1], 0xc0
	s_lshl_b32 s4, s4, 7
	v_and_b32_e32 v128, 0x70, v2
	v_lshl_add_u64 v[76:77], v[0:1], 0, v[128:129]
	v_add_u32_e32 v0, s4, v38
	v_ashrrev_i32_e32 v1, 31, v0
	v_lshlrev_b64 v[0:1], 11, v[0:1]
	s_waitcnt lgkmcnt(0)
	v_lshl_add_u64 v[0:1], s[48:49], 0, v[0:1]
	s_mov_b32 s6, 0x10000
	v_lshl_add_u64 v[78:79], v[0:1], 0, v[128:129]
	v_add_co_u32_e32 v0, vcc, s6, v76
	s_mov_b32 s7, 0x30000
	s_nop 0
	v_addc_co_u32_e32 v1, vcc, 0, v77, vcc
	v_add_co_u32_e32 v30, vcc, s6, v78
	s_mov_b32 s6, 0x20000
	s_nop 0
	v_addc_co_u32_e32 v31, vcc, 0, v79, vcc
	v_add_co_u32_e32 v32, vcc, s6, v78
	s_nop 0
	v_addc_co_u32_e32 v33, vcc, 0, v79, vcc
	v_add_co_u32_e32 v34, vcc, s7, v78
	s_nop 0
	v_addc_co_u32_e32 v35, vcc, 0, v79, vcc
	v_add_co_u32_e32 v36, vcc, s6, v76
	v_addc_co_u32_e32 v37, vcc, 0, v77, vcc
	s_barrier
	v_ashrrev_i32_e32 v30, 7, v90
	s_movk_i32 s8, 0x90
	v_and_b32_e32 v92, 15, v90
	v_bfe_u32 v91, v90, 4, 2
	v_and_b32_e32 v31, 0x4f, v90
	v_mul_lo_u32 v32, v38, s8
	v_mul_lo_u32 v93, v30, 48
	v_lshl_add_u32 v30, v91, 4, 16
	v_mul_u32_u24_e32 v31, 0x90, v31
	v_add3_u32 v94, v128, v32, 16
	v_or_b32_e32 v32, v93, v92
	v_mov_b32_e32 v0, 0
	v_add_u32_e32 v95, v30, v31
	v_mul_lo_u32 v31, v32, s8
	s_mov_b64 s[8:9], 0x10000
	s_mov_b64 s[10:11], 0x20000
	s_mov_b64 s[12:13], 0x30000
	s_mov_b32 s7, 0
	s_movk_i32 s6, 0x80
	v_mov_b32_e32 v1, v0
	v_add_u32_e32 v96, 0xd800, v94
	v_add_u32_e32 v97, v30, v31
	v_lshl_add_u64 v[80:81], v[78:79], 0, s[8:9]
	v_lshl_add_u64 v[82:83], v[78:79], 0, s[10:11]
	v_lshl_add_u64 v[84:85], v[78:79], 0, s[12:13]
	v_lshl_add_u64 v[86:87], v[76:77], 0, s[8:9]
	v_lshl_add_u64 v[88:89], v[76:77], 0, s[10:11]
	v_mov_b32_e32 v30, v0
	v_mov_b32_e32 v31, v0
	v_mov_b32_e32 v32, v0
	v_mov_b32_e32 v33, v0
	v_mov_b32_e32 v34, v0
	v_mov_b32_e32 v35, v0
	v_mov_b32_e32 v36, v0
	v_mov_b32_e32 v37, v0
	v_mov_b32_e32 v38, v0
	v_mov_b32_e32 v39, v0
	v_mov_b32_e32 v40, v0
	v_mov_b32_e32 v41, v0
	v_mov_b32_e32 v42, v0
	v_mov_b32_e32 v43, v0
	v_mov_b32_e32 v72, v0
	v_mov_b32_e32 v73, v0
	v_mov_b32_e32 v74, v0
	v_mov_b32_e32 v75, v0
	s_waitcnt vmcnt(12)
	s_waitcnt vmcnt(11)
	s_waitcnt vmcnt(10)
	s_waitcnt vmcnt(9)
	s_waitcnt vmcnt(8)
	s_waitcnt vmcnt(7)
	v_mov_b32_e32 v2, v0
	v_mov_b32_e32 v3, v0
	v_mov_b32_e32 v4, v0
	v_mov_b32_e32 v5, v0
	v_mov_b32_e32 v6, v0
	v_mov_b32_e32 v7, v0
	v_mov_b32_e32 v8, v0
	v_mov_b32_e32 v9, v0
	v_mov_b32_e32 v10, v0
	v_mov_b32_e32 v11, v0
	v_mov_b32_e32 v12, v0
	v_mov_b32_e32 v13, v0
	v_mov_b32_e32 v14, v0
	v_mov_b32_e32 v15, v0
	v_mov_b32_e32 v16, v0
	v_mov_b32_e32 v17, v0
	v_mov_b32_e32 v18, v0
	v_mov_b32_e32 v19, v0
	v_mov_b32_e32 v20, v0
	v_mov_b32_e32 v21, v0
	v_mov_b32_e32 v22, v0
	v_mov_b32_e32 v23, v0
	v_mov_b32_e32 v24, v0
	v_mov_b32_e32 v25, v0
	v_mov_b32_e32 v26, v0
	v_mov_b32_e32 v27, v0
	v_mov_b32_e32 v28, v0
	v_mov_b32_e32 v29, v0
	s_waitcnt lgkmcnt(0)
	s_barrier
	v_and_b32_e32 v204, 15, v168
	v_lshrrev_b32_e32 v205, 4, v168
	v_bfe_u32 v206, v168, 1, 3
	v_xor_b32_e32 v205, v205, v206
	v_lshlrev_b32_e32 v205, 4, v205
	v_readfirstlane_b32 s19, v162
	v_readfirstlane_b32 s8, v76
	v_readfirstlane_b32 s9, v77
	v_readfirstlane_b32 s10, v78
	v_readfirstlane_b32 s11, v79
	s_lshr_b32 s19, s19, 6
	s_lshr_b32 s16, s19, 1
	s_and_b32 s17, s19, 1
	s_mul_i32 s16, s16, 48
	v_add_u32_e32 v206, s16, v204
	v_lshl_add_u32 v232, v206, 7, v205
	v_xor_b32_e32 v233, 64, v232
	v_add_u32_e32 v232, 16, v232
	v_add_u32_e32 v233, 16, v233
	v_lshl_add_u32 v206, s17, 6, v204
	v_lshl_add_u32 v234, v206, 7, v205
	v_xor_b32_e32 v235, 64, v234
	v_add_u32_e32 v234, 0x3010, v234
	v_add_u32_e32 v235, 0x3010, v235
	v_lshrrev_b32_e32 v206, 3, v168
	v_and_b32_e32 v207, 7, v168
	v_lshrrev_b32_e32 v204, 1, v206
	v_xor_b32_e32 v207, v207, v204
	v_lshlrev_b32_e32 v207, 4, v207
	v_lshl_add_u32 v236, v206, 11, v207
	v_xor_b32_e32 v237, 64, v236
	s_and_b32 s17, s19, 1
	s_cmp_eq_u32 s17, 0
	s_cselect_b64 vcc, -1, 0
	s_nop 3
	v_cndmask_b32_e32 v238, v237, v236, vcc
	v_cndmask_b32_e32 v239, v236, v237, vcc
	s_mul_i32 s16, s19, 0x8000
	s_add_u32 s8, s8, s16
	s_addc_u32 s9, s9, 0
	s_mul_i32 s16, s19, 0xc000
	s_add_u32 s10, s10, s16
	s_addc_u32 s11, s11, 0
	s_mul_i32 s16, s19, 0xc00
	s_lshl_b32 s17, s19, 12
	s_add_i32 m0, s16, 0x10
	s_nop 0
	global_load_lds_dwordx4 v238, s[8:9]
	s_add_i32 m0, s16, 0x410
	s_add_u32 s12, s8, 0x4000
	s_addc_u32 s13, s9, 0
	global_load_lds_dwordx4 v239, s[12:13]
	s_add_i32 m0, s16, 0x810
	s_add_u32 s12, s8, 0x8000
	s_addc_u32 s13, s9, 0
	global_load_lds_dwordx4 v238, s[12:13]
	s_add_i32 m0, s17, 0x3010
	s_nop 0
	global_load_lds_dwordx4 v236, s[10:11]
	s_add_i32 m0, s17, 0x3410
	s_add_u32 s12, s10, 0x4000
	s_addc_u32 s13, s11, 0
	global_load_lds_dwordx4 v237, s[12:13]
	s_add_i32 m0, s17, 0x3810
	s_add_u32 s12, s10, 0x8000
	s_addc_u32 s13, s11, 0
	global_load_lds_dwordx4 v236, s[12:13]
	s_add_i32 m0, s17, 0x3c10
	s_add_u32 s12, s10, 0xc000
	s_addc_u32 s13, s11, 0
	global_load_lds_dwordx4 v237, s[12:13]
	s_mov_b32 s18, 0
	s_waitcnt vmcnt(0)
	s_barrier
	s_setprio 1
.LBB1_808:
	s_lshl_b32 s19, s18, 8
	s_add_i32 s19, s19, 0x80
	s_min_u32 s19, s19, 0x780
	s_add_u32 s40, s8, s19
	s_addc_u32 s41, s9, 0
	s_add_u32 s42, s10, s19
	s_addc_u32 s43, s11, 0
	ds_read_b128 v[142:145], v234 offset:0
	ds_read_b128 v[146:149], v234 offset:2048
	ds_read_b128 v[150:153], v234 offset:4096
	ds_read_b128 v[154:157], v234 offset:6144
	ds_read_b128 v[130:133], v232 offset:0
	ds_read_b128 v[134:137], v232 offset:2048
	ds_read_b128 v[138:141], v232 offset:4096
	ds_read_b128 v[216:219], v235 offset:0
	ds_read_b128 v[220:223], v235 offset:2048
	ds_read_b128 v[224:227], v235 offset:4096
	ds_read_b128 v[228:231], v235 offset:6144
	ds_read_b128 v[188:191], v233 offset:0
	ds_read_b128 v[192:195], v233 offset:2048
	ds_read_b128 v[196:199], v233 offset:4096
	s_waitcnt lgkmcnt(9)
	s_add_i32 m0, s16, 0x7010
	s_nop 0
	v_mfma_f32_16x16x32_bf16 v[72:75], v[142:145], v[130:133], v[72:75]
	global_load_lds_dwordx4 v238, s[40:41]
	s_add_i32 m0, s16, 0x7410
	s_add_u32 s12, s40, 0x4000
	s_addc_u32 s13, s41, 0
	v_mfma_f32_16x16x32_bf16 v[40:43], v[146:149], v[130:133], v[40:43]
	global_load_lds_dwordx4 v239, s[12:13]
	v_mfma_f32_16x16x32_bf16 v[36:39], v[150:153], v[130:133], v[36:39]
	v_mfma_f32_16x16x32_bf16 v[32:35], v[154:157], v[130:133], v[32:35]
	s_waitcnt lgkmcnt(8)
	s_add_i32 m0, s16, 0x7810
	s_add_u32 s12, s40, 0x8000
	s_addc_u32 s13, s41, 0
	v_mfma_f32_16x16x32_bf16 v[28:31], v[142:145], v[134:137], v[28:31]
	v_mfma_f32_16x16x32_bf16 v[24:27], v[146:149], v[134:137], v[24:27]
	global_load_lds_dwordx4 v238, s[12:13]
	v_mfma_f32_16x16x32_bf16 v[20:23], v[150:153], v[134:137], v[20:23]
	v_mfma_f32_16x16x32_bf16 v[16:19], v[154:157], v[134:137], v[16:19]
	s_waitcnt lgkmcnt(7)
	s_add_i32 m0, s17, 0xa010
	s_nop 0
	v_mfma_f32_16x16x32_bf16 v[12:15], v[142:145], v[138:141], v[12:15]
	v_mfma_f32_16x16x32_bf16 v[8:11], v[146:149], v[138:141], v[8:11]
	global_load_lds_dwordx4 v236, s[42:43]
	v_mfma_f32_16x16x32_bf16 v[4:7], v[150:153], v[138:141], v[4:7]
	v_mfma_f32_16x16x32_bf16 v[0:3], v[154:157], v[138:141], v[0:3]
	s_waitcnt lgkmcnt(2)
	s_add_i32 m0, s17, 0xa410
	s_add_u32 s12, s42, 0x4000
	s_addc_u32 s13, s43, 0
	v_mfma_f32_16x16x32_bf16 v[72:75], v[216:219], v[188:191], v[72:75]
	v_mfma_f32_16x16x32_bf16 v[40:43], v[220:223], v[188:191], v[40:43]
	global_load_lds_dwordx4 v237, s[12:13]
	v_mfma_f32_16x16x32_bf16 v[36:39], v[224:227], v[188:191], v[36:39]
	v_mfma_f32_16x16x32_bf16 v[32:35], v[228:231], v[188:191], v[32:35]
	s_waitcnt lgkmcnt(1)
	s_add_i32 m0, s17, 0xa810
	s_add_u32 s12, s42, 0x8000
	s_addc_u32 s13, s43, 0
	v_mfma_f32_16x16x32_bf16 v[28:31], v[216:219], v[192:195], v[28:31]
	v_mfma_f32_16x16x32_bf16 v[24:27], v[220:223], v[192:195], v[24:27]
	global_load_lds_dwordx4 v236, s[12:13]
	v_mfma_f32_16x16x32_bf16 v[20:23], v[224:227], v[192:195], v[20:23]
	v_mfma_f32_16x16x32_bf16 v[16:19], v[228:231], v[192:195], v[16:19]
	s_waitcnt lgkmcnt(0)
	s_add_i32 m0, s17, 0xac10
	s_add_u32 s12, s42, 0xc000
	s_addc_u32 s13, s43, 0
	v_mfma_f32_16x16x32_bf16 v[12:15], v[216:219], v[196:199], v[12:15]
	v_mfma_f32_16x16x32_bf16 v[8:11], v[220:223], v[196:199], v[8:11]
	global_load_lds_dwordx4 v237, s[12:13]
	v_mfma_f32_16x16x32_bf16 v[4:7], v[224:227], v[196:199], v[4:7]
	v_mfma_f32_16x16x32_bf16 v[0:3], v[228:231], v[196:199], v[0:3]
	s_waitcnt vmcnt(0)
	s_barrier
	s_lshl_b32 s19, s18, 8
	s_add_i32 s19, s19, 0x100
	s_min_u32 s19, s19, 0x780
	s_add_u32 s40, s8, s19
	s_addc_u32 s41, s9, 0
	s_add_u32 s42, s10, s19
	s_addc_u32 s43, s11, 0
	ds_read_b128 v[142:145], v234 offset:28672
	ds_read_b128 v[146:149], v234 offset:30720
	ds_read_b128 v[150:153], v234 offset:32768
	ds_read_b128 v[154:157], v234 offset:34816
	ds_read_b128 v[130:133], v232 offset:28672
	ds_read_b128 v[134:137], v232 offset:30720
	ds_read_b128 v[138:141], v232 offset:32768
	ds_read_b128 v[216:219], v235 offset:28672
	ds_read_b128 v[220:223], v235 offset:30720
	ds_read_b128 v[224:227], v235 offset:32768
	ds_read_b128 v[228:231], v235 offset:34816
	ds_read_b128 v[188:191], v233 offset:28672
	ds_read_b128 v[192:195], v233 offset:30720
	ds_read_b128 v[196:199], v233 offset:32768
	s_waitcnt lgkmcnt(9)
	s_add_i32 m0, s16, 0x10
	s_nop 0
	v_mfma_f32_16x16x32_bf16 v[72:75], v[142:145], v[130:133], v[72:75]
	global_load_lds_dwordx4 v238, s[40:41]
	s_add_i32 m0, s16, 0x410
	s_add_u32 s12, s40, 0x4000
	s_addc_u32 s13, s41, 0
	v_mfma_f32_16x16x32_bf16 v[40:43], v[146:149], v[130:133], v[40:43]
	global_load_lds_dwordx4 v239, s[12:13]
	v_mfma_f32_16x16x32_bf16 v[36:39], v[150:153], v[130:133], v[36:39]
	v_mfma_f32_16x16x32_bf16 v[32:35], v[154:157], v[130:133], v[32:35]
	s_waitcnt lgkmcnt(8)
	s_add_i32 m0, s16, 0x810
	s_add_u32 s12, s40, 0x8000
	s_addc_u32 s13, s41, 0
	v_mfma_f32_16x16x32_bf16 v[28:31], v[142:145], v[134:137], v[28:31]
	v_mfma_f32_16x16x32_bf16 v[24:27], v[146:149], v[134:137], v[24:27]
	global_load_lds_dwordx4 v238, s[12:13]
	v_mfma_f32_16x16x32_bf16 v[20:23], v[150:153], v[134:137], v[20:23]
	v_mfma_f32_16x16x32_bf16 v[16:19], v[154:157], v[134:137], v[16:19]
	s_waitcnt lgkmcnt(7)
	s_add_i32 m0, s17, 0x3010
	s_nop 0
	v_mfma_f32_16x16x32_bf16 v[12:15], v[142:145], v[138:141], v[12:15]
	v_mfma_f32_16x16x32_bf16 v[8:11], v[146:149], v[138:141], v[8:11]
	global_load_lds_dwordx4 v236, s[42:43]
	v_mfma_f32_16x16x32_bf16 v[4:7], v[150:153], v[138:141], v[4:7]
	v_mfma_f32_16x16x32_bf16 v[0:3], v[154:157], v[138:141], v[0:3]
	s_waitcnt lgkmcnt(2)
	s_add_i32 m0, s17, 0x3410
	s_add_u32 s12, s42, 0x4000
	s_addc_u32 s13, s43, 0
	v_mfma_f32_16x16x32_bf16 v[72:75], v[216:219], v[188:191], v[72:75]
	v_mfma_f32_16x16x32_bf16 v[40:43], v[220:223], v[188:191], v[40:43]
	global_load_lds_dwordx4 v237, s[12:13]
	v_mfma_f32_16x16x32_bf16 v[36:39], v[224:227], v[188:191], v[36:39]
	v_mfma_f32_16x16x32_bf16 v[32:35], v[228:231], v[188:191], v[32:35]
	s_waitcnt lgkmcnt(1)
	s_add_i32 m0, s17, 0x3810
	s_add_u32 s12, s42, 0x8000
	s_addc_u32 s13, s43, 0
	v_mfma_f32_16x16x32_bf16 v[28:31], v[216:219], v[192:195], v[28:31]
	v_mfma_f32_16x16x32_bf16 v[24:27], v[220:223], v[192:195], v[24:27]
	global_load_lds_dwordx4 v236, s[12:13]
	v_mfma_f32_16x16x32_bf16 v[20:23], v[224:227], v[192:195], v[20:23]
	v_mfma_f32_16x16x32_bf16 v[16:19], v[228:231], v[192:195], v[16:19]
	s_waitcnt lgkmcnt(0)
	s_add_i32 m0, s17, 0x3c10
	s_add_u32 s12, s42, 0xc000
	s_addc_u32 s13, s43, 0
	v_mfma_f32_16x16x32_bf16 v[12:15], v[216:219], v[196:199], v[12:15]
	v_mfma_f32_16x16x32_bf16 v[8:11], v[220:223], v[196:199], v[8:11]
	global_load_lds_dwordx4 v237, s[12:13]
	v_mfma_f32_16x16x32_bf16 v[4:7], v[224:227], v[196:199], v[4:7]
	v_mfma_f32_16x16x32_bf16 v[0:3], v[228:231], v[196:199], v[0:3]
	s_waitcnt vmcnt(0)
	s_barrier
	s_add_i32 s18, s18, 1
	s_cmp_eq_u32 s18, 8
	s_cbranch_scc0 .LBB1_808
	s_setprio 0
	s_waitcnt vmcnt(6)
	v_or_b32_e32 v45, s5, v92
	s_waitcnt vmcnt(4)
	v_add_u32_e32 v54, v45, v93
	v_and_b32_e32 v44, 64, v90
	v_lshlrev_b32_e32 v45, 2, v91
	v_ashrrev_i32_e32 v55, 31, v54
	s_waitcnt vmcnt(2)
	v_or3_b32 v60, v45, v44, s4
	v_lshlrev_b64 v[44:45], 14, v[54:55]
	v_lshl_add_u64 v[44:45], s[76:77], 0, v[44:45]
	s_mov_b64 s[4:5], 0x3800
	v_ashrrev_i32_e32 v61, 31, v60
	v_lshl_add_u64 v[58:59], v[44:45], 0, s[4:5]
	v_lshlrev_b64 v[50:51], 1, v[60:61]
	v_lshl_add_u64 v[44:45], v[58:59], 0, v[50:51]
	global_load_dwordx2 v[44:45], v[44:45], off
	v_lshlrev_b64 v[46:47], 12, v[54:55]
	v_lshl_add_u64 v[46:47], s[72:73], 0, v[46:47]
	s_waitcnt vmcnt(0)
	v_lshlrev_b32_e32 v52, 16, v44
	v_and_b32_e32 v53, 0xffff0000, v44
	v_lshlrev_b32_e32 v56, 16, v45
	v_and_b32_e32 v57, 0xffff0000, v45
	v_lshlrev_b64 v[44:45], 2, v[60:61]
	v_lshl_add_u64 v[48:49], s[14:15], 0, v[44:45]
	global_load_dwordx4 v[62:65], v[48:49], off
	s_waitcnt vmcnt(0)
	v_pk_add_f32 v[56:57], v[64:65], v[56:57]
	s_nop 0
	v_mul_f32_e32 v55, 0xbfb8aa3b, v56
	v_exp_f32_e32 v55, v55
	v_pk_add_f32 v[52:53], v[62:63], v[52:53]
	v_add_f32_e32 v55, 1.0, v55
	v_mul_f32_e32 v52, 0xbfb8aa3b, v52
	v_mul_f32_e32 v53, 0xbfb8aa3b, v53
	v_exp_f32_e32 v52, v52
	v_exp_f32_e32 v53, v53
	v_rcp_f32_e32 v56, v55
	v_mul_f32_e32 v55, 0xbfb8aa3b, v57
	v_exp_f32_e32 v55, v55
	v_add_f32_e32 v52, 1.0, v52
	v_add_f32_e32 v53, 1.0, v53
	v_rcp_f32_e32 v52, v52
	v_rcp_f32_e32 v53, v53
	v_add_f32_e32 v55, 1.0, v55
	v_rcp_f32_e32 v57, v55
	v_pk_mul_f32 v[62:63], v[72:73], v[52:53]
	v_or_b32_e32 v52, 16, v60
	v_ashrrev_i32_e32 v53, 31, v52
	v_pk_mul_f32 v[64:65], v[74:75], v[56:57]
	v_lshl_add_u64 v[56:57], v[46:47], 0, v[44:45]
	v_lshlrev_b64 v[46:47], 1, v[52:53]
	global_store_dwordx4 v[56:57], v[62:65], off
	v_lshl_add_u64 v[52:53], v[52:53], 2, s[14:15]
	s_nop 0
	v_lshl_add_u64 v[62:63], v[58:59], 0, v[46:47]
	global_load_dwordx2 v[62:63], v[62:63], off
	s_waitcnt vmcnt(0)
	v_lshlrev_b32_e32 v66, 16, v62
	v_and_b32_e32 v67, 0xffff0000, v62
	v_lshlrev_b32_e32 v68, 16, v63
	v_and_b32_e32 v69, 0xffff0000, v63
	global_load_dwordx4 v[62:65], v[52:53], off
	s_waitcnt vmcnt(0)
	v_pk_add_f32 v[62:63], v[62:63], v[66:67]
	s_nop 0
	v_mul_f32_e32 v55, 0xbfb8aa3b, v62
	v_exp_f32_e32 v55, v55
	v_pk_add_f32 v[64:65], v[64:65], v[68:69]
	v_add_f32_e32 v55, 1.0, v55
	v_rcp_f32_e32 v62, v55
	v_mul_f32_e32 v55, 0xbfb8aa3b, v63
	v_exp_f32_e32 v55, v55
	s_nop 0
	v_add_f32_e32 v55, 1.0, v55
	v_rcp_f32_e32 v63, v55
	v_mul_f32_e32 v55, 0xbfb8aa3b, v64
	v_exp_f32_e32 v55, v55
	v_pk_mul_f32 v[40:41], v[40:41], v[62:63]
	v_add_f32_e32 v55, 1.0, v55
	v_rcp_f32_e32 v64, v55
	v_mul_f32_e32 v55, 0xbfb8aa3b, v65
	v_exp_f32_e32 v55, v55
	s_nop 0
	v_add_f32_e32 v55, 1.0, v55
	v_rcp_f32_e32 v65, v55
	s_nop 0
	v_pk_mul_f32 v[42:43], v[42:43], v[64:65]
	global_store_dwordx4 v[56:57], v[40:43], off offset:64
	s_nop 1
	v_or_b32_e32 v42, 32, v60
	v_ashrrev_i32_e32 v43, 31, v42
	v_lshlrev_b64 v[40:41], 1, v[42:43]
	v_lshl_add_u64 v[62:63], v[58:59], 0, v[40:41]
	global_load_dwordx2 v[62:63], v[62:63], off
	v_lshl_add_u64 v[42:43], v[42:43], 2, s[14:15]
	s_waitcnt vmcnt(0)
	v_lshlrev_b32_e32 v66, 16, v62
	v_and_b32_e32 v67, 0xffff0000, v62
	v_lshlrev_b32_e32 v68, 16, v63
	v_and_b32_e32 v69, 0xffff0000, v63
	global_load_dwordx4 v[62:65], v[42:43], off
	s_waitcnt vmcnt(0)
	v_pk_add_f32 v[62:63], v[62:63], v[66:67]
	s_nop 0
	v_mul_f32_e32 v55, 0xbfb8aa3b, v62
	v_exp_f32_e32 v55, v55
	v_pk_add_f32 v[64:65], v[64:65], v[68:69]
	v_add_f32_e32 v55, 1.0, v55
	v_rcp_f32_e32 v62, v55
	v_mul_f32_e32 v55, 0xbfb8aa3b, v63
	v_exp_f32_e32 v55, v55
	s_nop 0
	v_add_f32_e32 v55, 1.0, v55
	v_rcp_f32_e32 v63, v55
	v_mul_f32_e32 v55, 0xbfb8aa3b, v64
	v_exp_f32_e32 v55, v55
	v_pk_mul_f32 v[36:37], v[36:37], v[62:63]
	v_add_f32_e32 v55, 1.0, v55
	v_rcp_f32_e32 v64, v55
	v_mul_f32_e32 v55, 0xbfb8aa3b, v65
	v_exp_f32_e32 v55, v55
	s_nop 0
	v_add_f32_e32 v55, 1.0, v55
	v_rcp_f32_e32 v65, v55
	s_nop 0
	v_pk_mul_f32 v[38:39], v[38:39], v[64:65]
	global_store_dwordx4 v[56:57], v[36:39], off offset:128
	s_nop 1
	v_or_b32_e32 v38, 48, v60
	v_ashrrev_i32_e32 v39, 31, v38
	v_lshlrev_b64 v[36:37], 1, v[38:39]
	v_lshl_add_u64 v[58:59], v[58:59], 0, v[36:37]
	global_load_dwordx2 v[58:59], v[58:59], off
	v_lshl_add_u64 v[38:39], v[38:39], 2, s[14:15]
	s_waitcnt vmcnt(0)
	v_lshlrev_b32_e32 v62, 16, v58
	v_and_b32_e32 v63, 0xffff0000, v58
	v_lshlrev_b32_e32 v64, 16, v59
	v_and_b32_e32 v65, 0xffff0000, v59
	global_load_dwordx4 v[58:61], v[38:39], off
	s_waitcnt vmcnt(0)
	v_pk_add_f32 v[58:59], v[58:59], v[62:63]
	s_nop 0
	v_mul_f32_e32 v55, 0xbfb8aa3b, v58
	v_exp_f32_e32 v55, v55
	v_pk_add_f32 v[60:61], v[60:61], v[64:65]
	v_add_f32_e32 v55, 1.0, v55
	v_rcp_f32_e32 v58, v55
	v_mul_f32_e32 v55, 0xbfb8aa3b, v59
	v_exp_f32_e32 v55, v55
	s_nop 0
	v_add_f32_e32 v55, 1.0, v55
	v_rcp_f32_e32 v59, v55
	v_mul_f32_e32 v55, 0xbfb8aa3b, v60
	v_exp_f32_e32 v55, v55
	v_pk_mul_f32 v[32:33], v[32:33], v[58:59]
	v_add_f32_e32 v55, 1.0, v55
	v_rcp_f32_e32 v60, v55
	v_mul_f32_e32 v55, 0xbfb8aa3b, v61
	v_exp_f32_e32 v55, v55
	s_nop 0
	v_add_f32_e32 v55, 1.0, v55
	v_rcp_f32_e32 v61, v55
	s_nop 0
	v_pk_mul_f32 v[34:35], v[34:35], v[60:61]
	global_store_dwordx4 v[56:57], v[32:35], off offset:192
	global_load_dwordx4 v[56:59], v[48:49], off
	s_nop 0
	v_add_u32_e32 v32, 16, v54
	v_ashrrev_i32_e32 v33, 31, v32
	v_lshlrev_b64 v[34:35], 14, v[32:33]
	v_lshlrev_b64 v[60:61], 12, v[32:33]
	v_lshl_add_u64 v[32:33], s[76:77], 0, v[34:35]
	v_lshl_add_u64 v[32:33], v[32:33], 0, s[4:5]
	v_lshl_add_u64 v[34:35], v[32:33], 0, v[50:51]
	global_load_dwordx2 v[34:35], v[34:35], off
	s_waitcnt vmcnt(0)
	v_lshlrev_b32_e32 v62, 16, v34
	v_and_b32_e32 v63, 0xffff0000, v34
	v_pk_add_f32 v[56:57], v[56:57], v[62:63]
	v_lshlrev_b32_e32 v34, 16, v35
	v_mul_f32_e32 v55, 0xbfb8aa3b, v56
	v_exp_f32_e32 v55, v55
	v_and_b32_e32 v35, 0xffff0000, v35
	v_pk_add_f32 v[34:35], v[58:59], v[34:35]
	v_add_f32_e32 v55, 1.0, v55
	v_rcp_f32_e32 v56, v55
	v_mul_f32_e32 v55, 0xbfb8aa3b, v57
	v_exp_f32_e32 v55, v55
	v_mul_f32_e32 v34, 0xbfb8aa3b, v34
	v_mul_f32_e32 v35, 0xbfb8aa3b, v35
	v_exp_f32_e32 v34, v34
	v_exp_f32_e32 v35, v35
	v_add_f32_e32 v55, 1.0, v55
	v_rcp_f32_e32 v57, v55
	v_add_f32_e32 v34, 1.0, v34
	v_add_f32_e32 v35, 1.0, v35
	v_rcp_f32_e32 v34, v34
	v_rcp_f32_e32 v35, v35
	v_pk_mul_f32 v[56:57], v[28:29], v[56:57]
	v_lshl_add_u64 v[28:29], s[72:73], 0, v[60:61]
	v_lshl_add_u64 v[28:29], v[28:29], 0, v[44:45]
	v_pk_mul_f32 v[58:59], v[30:31], v[34:35]
	global_store_dwordx4 v[28:29], v[56:59], off
	v_lshl_add_u64 v[30:31], v[32:33], 0, v[46:47]
	global_load_dwordx2 v[30:31], v[30:31], off
	s_waitcnt vmcnt(0)
	v_lshlrev_b32_e32 v34, 16, v30
	global_load_dwordx4 v[56:59], v[52:53], off
	v_and_b32_e32 v35, 0xffff0000, v30
	v_lshlrev_b32_e32 v30, 16, v31
	v_and_b32_e32 v31, 0xffff0000, v31
	s_waitcnt vmcnt(0)
	v_pk_add_f32 v[30:31], v[58:59], v[30:31]
	v_pk_add_f32 v[34:35], v[56:57], v[34:35]
	v_mul_f32_e32 v30, 0xbfb8aa3b, v30
	v_mul_f32_e32 v34, 0xbfb8aa3b, v34
	v_mul_f32_e32 v35, 0xbfb8aa3b, v35
	v_mul_f32_e32 v31, 0xbfb8aa3b, v31
	v_exp_f32_e32 v34, v34
	v_exp_f32_e32 v35, v35
	v_exp_f32_e32 v30, v30
	v_exp_f32_e32 v31, v31
	v_add_f32_e32 v34, 1.0, v34
	v_add_f32_e32 v35, 1.0, v35
	v_add_f32_e32 v30, 1.0, v30
	v_add_f32_e32 v31, 1.0, v31
	v_rcp_f32_e32 v34, v34
	v_rcp_f32_e32 v35, v35
	v_rcp_f32_e32 v30, v30
	v_rcp_f32_e32 v31, v31
	v_pk_mul_f32 v[24:25], v[24:25], v[34:35]
	v_pk_mul_f32 v[26:27], v[26:27], v[30:31]
	global_store_dwordx4 v[28:29], v[24:27], off offset:64
	s_nop 1
	v_lshl_add_u64 v[24:25], v[32:33], 0, v[40:41]
	global_load_dwordx2 v[24:25], v[24:25], off
	s_waitcnt vmcnt(0)
	v_lshlrev_b32_e32 v30, 16, v24
	v_and_b32_e32 v31, 0xffff0000, v24
	v_lshlrev_b32_e32 v34, 16, v25
	v_and_b32_e32 v35, 0xffff0000, v25
	global_load_dwordx4 v[24:27], v[42:43], off
	s_waitcnt vmcnt(0)
	v_pk_add_f32 v[26:27], v[26:27], v[34:35]
	v_pk_add_f32 v[24:25], v[24:25], v[30:31]
	v_mul_f32_e32 v26, 0xbfb8aa3b, v26
	v_mul_f32_e32 v24, 0xbfb8aa3b, v24
	v_mul_f32_e32 v25, 0xbfb8aa3b, v25
	v_mul_f32_e32 v27, 0xbfb8aa3b, v27
	v_exp_f32_e32 v24, v24
	v_exp_f32_e32 v25, v25
	v_exp_f32_e32 v26, v26
	v_exp_f32_e32 v27, v27
	v_add_f32_e32 v24, 1.0, v24
	v_add_f32_e32 v25, 1.0, v25
	v_add_f32_e32 v26, 1.0, v26
	v_add_f32_e32 v27, 1.0, v27
	v_rcp_f32_e32 v24, v24
	v_rcp_f32_e32 v25, v25
	v_rcp_f32_e32 v26, v26
	v_rcp_f32_e32 v27, v27
	v_pk_mul_f32 v[20:21], v[20:21], v[24:25]
	v_pk_mul_f32 v[22:23], v[22:23], v[26:27]
	global_store_dwordx4 v[28:29], v[20:23], off offset:128
	s_nop 1
	v_lshl_add_u64 v[20:21], v[32:33], 0, v[36:37]
	global_load_dwordx2 v[20:21], v[20:21], off
	s_waitcnt vmcnt(0)
	v_lshlrev_b32_e32 v24, 16, v20
	v_and_b32_e32 v25, 0xffff0000, v20
	v_lshlrev_b32_e32 v26, 16, v21
	v_and_b32_e32 v27, 0xffff0000, v21
	global_load_dwordx4 v[20:23], v[38:39], off
	s_waitcnt vmcnt(0)
	v_pk_add_f32 v[22:23], v[22:23], v[26:27]
	v_pk_add_f32 v[20:21], v[20:21], v[24:25]
	v_mul_f32_e32 v22, 0xbfb8aa3b, v22
	v_mul_f32_e32 v20, 0xbfb8aa3b, v20
	v_mul_f32_e32 v21, 0xbfb8aa3b, v21
	v_mul_f32_e32 v23, 0xbfb8aa3b, v23
	v_exp_f32_e32 v20, v20
	v_exp_f32_e32 v21, v21
	v_exp_f32_e32 v22, v22
	v_exp_f32_e32 v23, v23
	v_add_f32_e32 v20, 1.0, v20
	v_add_f32_e32 v21, 1.0, v21
	v_add_f32_e32 v22, 1.0, v22
	v_add_f32_e32 v23, 1.0, v23
	v_rcp_f32_e32 v20, v20
	v_rcp_f32_e32 v21, v21
	v_rcp_f32_e32 v22, v22
	v_rcp_f32_e32 v23, v23
	v_pk_mul_f32 v[16:17], v[16:17], v[20:21]
	v_pk_mul_f32 v[18:19], v[18:19], v[22:23]
	global_store_dwordx4 v[28:29], v[16:19], off offset:192
	s_nop 1
	v_add_u32_e32 v16, 32, v54
	v_ashrrev_i32_e32 v17, 31, v16
	v_lshlrev_b64 v[18:19], 14, v[16:17]
	v_lshlrev_b64 v[22:23], 12, v[16:17]
	v_lshl_add_u64 v[16:17], s[76:77], 0, v[18:19]
	v_lshl_add_u64 v[16:17], v[16:17], 0, s[4:5]
	v_lshl_add_u64 v[18:19], v[16:17], 0, v[50:51]
	global_load_dwordx2 v[18:19], v[18:19], off
	v_readlane_b32 s4, v242, 63
	s_add_i32 s2, s2, s4
	s_cmpk_gt_i32 s2, 0x57f
	s_waitcnt vmcnt(0)
	v_lshlrev_b32_e32 v24, 16, v18
	v_and_b32_e32 v25, 0xffff0000, v18
	v_lshlrev_b32_e32 v26, 16, v19
	v_and_b32_e32 v27, 0xffff0000, v19
	global_load_dwordx4 v[18:21], v[48:49], off
	s_waitcnt vmcnt(0)
	v_pk_add_f32 v[18:19], v[18:19], v[24:25]
	v_pk_add_f32 v[20:21], v[20:21], v[26:27]
	v_mul_f32_e32 v18, 0xbfb8aa3b, v18
	v_mul_f32_e32 v19, 0xbfb8aa3b, v19
	v_exp_f32_e32 v18, v18
	v_exp_f32_e32 v19, v19
	v_mul_f32_e32 v20, 0xbfb8aa3b, v20
	v_mul_f32_e32 v21, 0xbfb8aa3b, v21
	v_exp_f32_e32 v20, v20
	v_exp_f32_e32 v21, v21
	v_add_f32_e32 v18, 1.0, v18
	v_add_f32_e32 v19, 1.0, v19
	v_rcp_f32_e32 v18, v18
	v_rcp_f32_e32 v19, v19
	v_add_f32_e32 v20, 1.0, v20
	v_add_f32_e32 v21, 1.0, v21
	v_rcp_f32_e32 v20, v20
	v_rcp_f32_e32 v21, v21
	v_pk_mul_f32 v[18:19], v[12:13], v[18:19]
	v_lshl_add_u64 v[12:13], s[72:73], 0, v[22:23]
	v_lshl_add_u64 v[12:13], v[12:13], 0, v[44:45]
	v_pk_mul_f32 v[20:21], v[14:15], v[20:21]
	global_store_dwordx4 v[12:13], v[18:21], off
	v_lshl_add_u64 v[14:15], v[16:17], 0, v[46:47]
	global_load_dwordx2 v[14:15], v[14:15], off
	s_waitcnt vmcnt(0)
	v_lshlrev_b32_e32 v22, 16, v14
	global_load_dwordx4 v[18:21], v[52:53], off
	v_and_b32_e32 v23, 0xffff0000, v14
	v_lshlrev_b32_e32 v14, 16, v15
	v_and_b32_e32 v15, 0xffff0000, v15
	s_waitcnt vmcnt(0)
	v_pk_add_f32 v[14:15], v[20:21], v[14:15]
	v_pk_add_f32 v[18:19], v[18:19], v[22:23]
	v_mul_f32_e32 v14, 0xbfb8aa3b, v14
	v_mul_f32_e32 v18, 0xbfb8aa3b, v18
	v_mul_f32_e32 v19, 0xbfb8aa3b, v19
	v_mul_f32_e32 v15, 0xbfb8aa3b, v15
	v_exp_f32_e32 v18, v18
	v_exp_f32_e32 v19, v19
	v_exp_f32_e32 v14, v14
	v_exp_f32_e32 v15, v15
	v_add_f32_e32 v18, 1.0, v18
	v_add_f32_e32 v19, 1.0, v19
	v_add_f32_e32 v14, 1.0, v14
	v_add_f32_e32 v15, 1.0, v15
	v_rcp_f32_e32 v18, v18
	v_rcp_f32_e32 v19, v19
	v_rcp_f32_e32 v14, v14
	v_rcp_f32_e32 v15, v15
	v_pk_mul_f32 v[8:9], v[8:9], v[18:19]
	v_pk_mul_f32 v[10:11], v[10:11], v[14:15]
	global_store_dwordx4 v[12:13], v[8:11], off offset:64
	s_nop 1
	v_lshl_add_u64 v[8:9], v[16:17], 0, v[40:41]
	global_load_dwordx2 v[8:9], v[8:9], off
	s_waitcnt vmcnt(0)
	v_lshlrev_b32_e32 v14, 16, v8
	v_and_b32_e32 v15, 0xffff0000, v8
	v_lshlrev_b32_e32 v18, 16, v9
	v_and_b32_e32 v19, 0xffff0000, v9
	global_load_dwordx4 v[8:11], v[42:43], off
	s_waitcnt vmcnt(0)
	v_pk_add_f32 v[10:11], v[10:11], v[18:19]
	v_pk_add_f32 v[8:9], v[8:9], v[14:15]
	v_mul_f32_e32 v10, 0xbfb8aa3b, v10
	v_mul_f32_e32 v8, 0xbfb8aa3b, v8
	v_mul_f32_e32 v9, 0xbfb8aa3b, v9
	v_mul_f32_e32 v11, 0xbfb8aa3b, v11
	v_exp_f32_e32 v8, v8
	v_exp_f32_e32 v9, v9
	v_exp_f32_e32 v10, v10
	v_exp_f32_e32 v11, v11
	v_add_f32_e32 v8, 1.0, v8
	v_add_f32_e32 v9, 1.0, v9
	v_add_f32_e32 v10, 1.0, v10
	v_add_f32_e32 v11, 1.0, v11
	v_rcp_f32_e32 v8, v8
	v_rcp_f32_e32 v9, v9
	v_rcp_f32_e32 v10, v10
	v_rcp_f32_e32 v11, v11
	v_pk_mul_f32 v[4:5], v[4:5], v[8:9]
	v_pk_mul_f32 v[6:7], v[6:7], v[10:11]
	global_store_dwordx4 v[12:13], v[4:7], off offset:128
	s_nop 1
	v_lshl_add_u64 v[4:5], v[16:17], 0, v[36:37]
	global_load_dwordx2 v[4:5], v[4:5], off
	s_waitcnt vmcnt(0)
	v_lshlrev_b32_e32 v8, 16, v4
	v_and_b32_e32 v9, 0xffff0000, v4
	v_lshlrev_b32_e32 v10, 16, v5
	v_and_b32_e32 v11, 0xffff0000, v5
	global_load_dwordx4 v[4:7], v[38:39], off
	s_waitcnt vmcnt(0)
	v_pk_add_f32 v[6:7], v[6:7], v[10:11]
	v_pk_add_f32 v[4:5], v[4:5], v[8:9]
	v_mul_f32_e32 v6, 0xbfb8aa3b, v6
	v_mul_f32_e32 v4, 0xbfb8aa3b, v4
	v_mul_f32_e32 v5, 0xbfb8aa3b, v5
	v_mul_f32_e32 v7, 0xbfb8aa3b, v7
	v_exp_f32_e32 v4, v4
	v_exp_f32_e32 v5, v5
	v_exp_f32_e32 v6, v6
	v_exp_f32_e32 v7, v7
	v_add_f32_e32 v4, 1.0, v4
	v_add_f32_e32 v5, 1.0, v5
	v_add_f32_e32 v6, 1.0, v6
	v_add_f32_e32 v7, 1.0, v7
	v_rcp_f32_e32 v4, v4
	v_rcp_f32_e32 v5, v5
	v_rcp_f32_e32 v6, v6
	v_rcp_f32_e32 v7, v7
	v_pk_mul_f32 v[0:1], v[0:1], v[4:5]
	v_pk_mul_f32 v[2:3], v[2:3], v[6:7]
	global_store_dwordx4 v[12:13], v[0:3], off offset:192
	s_cbranch_scc0 .LBB1_807
